# gate phase: third-round sample units split by channel group across 128 workgroups (was 32 workgroups x 4 groups)
# baseline (speedup 1.0000x reference)
.LBB0_733:
	s_or_b64 exec, exec, s[6:7]
	s_waitcnt lgkmcnt(0)
	s_barrier
	s_load_dwordx2 s[42:43], s[0:1], 0xd8
	s_cmpk_gt_i32 s2, 0x21f
	s_cbranch_scc1 .LBB0_802
	v_mbcnt_hi_u32_b32 v114, -1, v182
	s_lshl_b32 s6, s2, 4
	v_and_b32_e32 v0, 64, v114
	s_add_i32 s3, s6, 0xffffe000
	s_lshl_b32 s31, s34, 4
	s_add_i32 s40, s6, 0xffffe010
	s_add_i32 s41, s6, 0xffffe020
	s_add_i32 s62, s6, 0xffffe030
	s_add_i32 s63, s6, 0xffffe040
	s_add_i32 s64, s6, 0xffffe050
	s_add_i32 s65, s6, 0xffffe060
	s_add_i32 s66, s6, 0xffffe070
	v_mov_b32_e32 v65, 0
	v_mov_b32_e32 v112, 0x3727c5ac
	s_mov_b32 s67, 0xf800000
	v_mov_b32_e32 v113, 0x260
	s_movk_i32 s68, 0x220
	s_mov_b64 s[44:45], 0x26c00000
	s_mov_b64 s[46:47], 0x1eb00080
	s_mov_b64 s[48:49], 0x200
	s_mov_b64 s[50:51], 0x8000
	v_add_u32_e32 v115, 64, v0
	v_xor_b32_e32 v116, 1, v114
	v_xor_b32_e32 v117, 2, v114
	v_xor_b32_e32 v118, 4, v114
	v_xor_b32_e32 v119, 8, v114
	v_xor_b32_e32 v120, 16, v114
	v_xor_b32_e32 v121, 32, v114
	s_mov_b32 s69, s2
	s_mov_b32 s98, 0
	s_movk_i32 s99, 0x1000
	s_branch .LBB0_736
.LBB0_735:
	s_add_i32 s69, s69, s34
	s_add_i32 s3, s3, s31
	s_add_i32 s40, s40, s31
	s_add_i32 s41, s41, s31
	s_add_i32 s62, s62, s31
	s_add_i32 s63, s63, s31
	s_add_i32 s64, s64, s31
	s_add_i32 s65, s65, s31
	s_add_i32 s66, s66, s31
	s_cmpk_lt_i32 s69, 0x200
	s_cbranch_scc1 .Lgt_go
	s_cmpk_gt_i32 s69, 0x27f
	s_cbranch_scc1 .LBB0_802
	s_sub_i32 s100, s69, 0x200
	s_and_b32 s98, s100, 3
	s_lshr_b32 s100, s100, 2
	s_add_i32 s69, s100, 0x200
	s_lshl_b32 s3, s69, 4
	s_add_i32 s3, s3, 0xffffe000
	s_add_i32 s40, s3, 16
	s_add_i32 s41, s3, 32
	s_add_i32 s62, s3, 48
	s_add_i32 s63, s3, 64
	s_add_i32 s64, s3, 0x50
	s_add_i32 s65, s3, 0x60
	s_add_i32 s66, s3, 0x70
	s_lshl_b32 s99, s98, 10
	s_add_i32 s99, s99, 0x400
.Lgt_go:
.LBB0_736:
	v_mov_b32_e32 v1, v194
	s_lshl_b32 s6, s69, 4
	v_readfirstlane_b32 s14, v1
	s_ashr_i32 s10, s14, 6
	s_add_i32 s8, s6, 0xe000
	s_lshl_b32 s9, s69, 7
	s_cmpk_gt_i32 s69, 0x1ff
	s_cselect_b64 s[52:53], -1, 0
	s_and_b64 s[6:7], s[52:53], exec
	s_cselect_b32 s24, 16, 0x80
	s_cselect_b32 s70, s8, s9
	s_lshl_b32 s15, s10, 4
	s_add_i32 s8, s70, s15
	s_ashr_i32 s9, s8, 31
	s_lshl_b64 s[8:9], s[8:9], 11
	v_and_b32_e32 v0, 63, v1
	s_load_dwordx4 s[36:39], s[0:1], 0x60
	s_load_dwordx2 s[26:27], s[0:1], 0x78
	s_waitcnt lgkmcnt(0)
	s_add_u32 s8, s42, s8
	v_lshlrev_b32_e32 v64, 4, v0
	s_addc_u32 s9, s43, s9
	v_lshl_add_u64 v[2:3], s[8:9], 0, v[64:65]
	s_lshl_b32 s8, s10, 7
	s_add_i32 s8, s8, 0
	v_cmp_eq_u32_e64 s[6:7], 0, v0
	s_add_i32 s16, s8, 0x20004
	s_cmp_ge_i32 s15, s24
	s_cbranch_scc1 .Lgst_done
	v_add_co_u32_e32 v60, vcc, 0x26c00000, v2
	s_nop 1
	v_addc_co_u32_e32 v61, vcc, 0, v3, vcc
	global_load_dwordx4 v[28:31], v[60:61], off
	global_load_dwordx4 v[32:35], v[60:61], off offset:1024
	global_load_dwordx4 v[36:39], v[60:61], off offset:2048
	global_load_dwordx4 v[40:43], v[60:61], off offset:3072
	v_add_co_u32_e32 v60, vcc, 0x1000, v60
	s_nop 1
	v_addc_co_u32_e32 v61, vcc, 0, v61, vcc
	global_load_dwordx4 v[44:47], v[60:61], off
	global_load_dwordx4 v[48:51], v[60:61], off offset:1024
	global_load_dwordx4 v[52:55], v[60:61], off offset:2048
	global_load_dwordx4 v[56:59], v[60:61], off offset:3072
	v_add_co_u32_e32 v60, vcc, 0x1000, v60
	s_nop 1
	v_addc_co_u32_e32 v61, vcc, 0, v61, vcc
	global_load_dwordx4 v[66:69], v[60:61], off
	global_load_dwordx4 v[70:73], v[60:61], off offset:1024
	global_load_dwordx4 v[74:77], v[60:61], off offset:2048
	global_load_dwordx4 v[78:81], v[60:61], off offset:3072
	v_add_co_u32_e32 v60, vcc, 0x1000, v60
	s_nop 1
	v_addc_co_u32_e32 v61, vcc, 0, v61, vcc
	global_load_dwordx4 v[82:85], v[60:61], off
	global_load_dwordx4 v[86:89], v[60:61], off offset:1024
	global_load_dwordx4 v[90:93], v[60:61], off offset:2048
	global_load_dwordx4 v[94:97], v[60:61], off offset:3072
	v_add_co_u32_e32 v60, vcc, 0x1000, v60
	s_nop 1
	v_addc_co_u32_e32 v61, vcc, 0, v61, vcc
	global_load_dwordx4 v[98:101], v[60:61], off
	global_load_dwordx4 v[102:105], v[60:61], off offset:1024
	global_load_dwordx4 v[122:125], v[60:61], off offset:2048
	global_load_dwordx4 v[126:129], v[60:61], off offset:3072
	v_add_co_u32_e32 v60, vcc, 0x1000, v60
	s_nop 1
	v_addc_co_u32_e32 v61, vcc, 0, v61, vcc
	global_load_dwordx4 v[130:133], v[60:61], off
	global_load_dwordx4 v[134:137], v[60:61], off offset:1024
	global_load_dwordx4 v[138:141], v[60:61], off offset:2048
	global_load_dwordx4 v[142:145], v[60:61], off offset:3072
	v_add_co_u32_e32 v60, vcc, 0x1000, v60
	s_nop 1
	v_addc_co_u32_e32 v61, vcc, 0, v61, vcc
	global_load_dwordx4 v[146:149], v[60:61], off
	global_load_dwordx4 v[150:153], v[60:61], off offset:1024
	global_load_dwordx4 v[154:157], v[60:61], off offset:2048
	global_load_dwordx4 v[158:161], v[60:61], off offset:3072
	v_add_co_u32_e32 v60, vcc, 0x1000, v60
	s_nop 1
	v_addc_co_u32_e32 v61, vcc, 0, v61, vcc
	global_load_dwordx4 v[162:165], v[60:61], off
	global_load_dwordx4 v[166:169], v[60:61], off offset:1024
	global_load_dwordx4 v[170:173], v[60:61], off offset:2048
	global_load_dwordx4 v[174:177], v[60:61], off offset:3072
	s_add_i32 s8, s16, -4
	v_mov_b32_e32 v62, s8
	s_waitcnt vmcnt(30)
	v_mov_b32_e32 v4, v28
	v_mov_b32_e32 v5, v29
	v_mov_b32_e32 v6, v30
	v_mov_b32_e32 v7, v31
	v_mov_b32_e32 v8, v32
	v_mov_b32_e32 v9, v33
	v_mov_b32_e32 v10, v34
	v_mov_b32_e32 v11, v35
	v_lshlrev_b32_e32 v13, 16, v4
	v_and_b32_e32 v14, 0xffff0000, v4
	v_lshlrev_b32_e32 v15, 16, v5
	v_and_b32_e32 v5, 0xffff0000, v5
	v_lshlrev_b32_e32 v16, 16, v6
	v_and_b32_e32 v6, 0xffff0000, v6
	v_lshlrev_b32_e32 v17, 16, v7
	v_and_b32_e32 v7, 0xffff0000, v7
	v_lshlrev_b32_e32 v18, 16, v8
	v_and_b32_e32 v8, 0xffff0000, v8
	v_lshlrev_b32_e32 v19, 16, v9
	v_and_b32_e32 v9, 0xffff0000, v9
	v_lshlrev_b32_e32 v20, 16, v10
	v_and_b32_e32 v10, 0xffff0000, v10
	v_lshlrev_b32_e32 v21, 16, v11
	v_and_b32_e32 v11, 0xffff0000, v11
	v_add_f32_e32 v22, v13, v14
	v_add_f32_e32 v23, v15, v5
	v_add_f32_e32 v24, v16, v6
	v_add_f32_e32 v25, v17, v7
	v_add_f32_e32 v26, v18, v8
	v_add_f32_e32 v27, v19, v9
	v_add_f32_e32 v12, v20, v10
	v_add_f32_e32 v4, v21, v11
	v_add_f32_e32 v22, v22, v23
	v_add_f32_e32 v24, v24, v25
	v_add_f32_e32 v26, v26, v27
	v_add_f32_e32 v4, v12, v4
	v_add_f32_e32 v22, v22, v24
	v_add_f32_e32 v4, v26, v4
	v_add_f32_e32 v4, v22, v4
	s_nop 1
	v_add_f32_dpp v4, v4, v4 row_ror:8 row_mask:0xf bank_mask:0xf bound_ctrl:1
	s_nop 1
	v_add_f32_dpp v4, v4, v4 row_ror:4 row_mask:0xf bank_mask:0xf bound_ctrl:1
	s_nop 1
	v_add_f32_dpp v4, v4, v4 row_ror:2 row_mask:0xf bank_mask:0xf bound_ctrl:1
	s_nop 1
	v_add_f32_dpp v4, v4, v4 row_ror:1 row_mask:0xf bank_mask:0xf bound_ctrl:1
	v_mov_b32_e32 v22, v4
	s_nop 1
	v_permlane16_swap_b32_e32 v4, v22
	v_add_f32_e32 v4, v4, v22
	v_mov_b32_e32 v22, v4
	s_nop 1
	v_permlane32_swap_b32_e32 v4, v22
	v_add_f32_e32 v4, v4, v22
	v_fmac_f32_e32 v13, 0xba800000, v4
	v_fmac_f32_e32 v14, 0xba800000, v4
	v_fmac_f32_e32 v15, 0xba800000, v4
	v_fmac_f32_e32 v5, 0xba800000, v4
	v_fmac_f32_e32 v16, 0xba800000, v4
	v_fmac_f32_e32 v6, 0xba800000, v4
	v_fmac_f32_e32 v17, 0xba800000, v4
	v_fmac_f32_e32 v7, 0xba800000, v4
	v_fmac_f32_e32 v18, 0xba800000, v4
	v_fmac_f32_e32 v8, 0xba800000, v4
	v_fmac_f32_e32 v19, 0xba800000, v4
	v_fmac_f32_e32 v9, 0xba800000, v4
	v_fmac_f32_e32 v20, 0xba800000, v4
	v_fmac_f32_e32 v10, 0xba800000, v4
	v_fmac_f32_e32 v21, 0xba800000, v4
	v_fmac_f32_e32 v11, 0xba800000, v4
	v_mul_f32_e32 v23, v13, v13
	v_fmac_f32_e32 v23, v14, v14
	v_fmac_f32_e32 v23, v15, v15
	v_fmac_f32_e32 v23, v5, v5
	v_fmac_f32_e32 v23, v16, v16
	v_fmac_f32_e32 v23, v6, v6
	v_fmac_f32_e32 v23, v17, v17
	v_fmac_f32_e32 v23, v7, v7
	v_fmac_f32_e32 v23, v18, v18
	v_fmac_f32_e32 v23, v8, v8
	v_fmac_f32_e32 v23, v19, v19
	v_fmac_f32_e32 v23, v9, v9
	v_fmac_f32_e32 v23, v20, v20
	v_fmac_f32_e32 v23, v10, v10
	v_fmac_f32_e32 v23, v21, v21
	v_fmac_f32_e32 v23, v11, v11
	s_nop 1
	v_add_f32_dpp v23, v23, v23 row_ror:8 row_mask:0xf bank_mask:0xf bound_ctrl:1
	s_nop 1
	v_add_f32_dpp v23, v23, v23 row_ror:4 row_mask:0xf bank_mask:0xf bound_ctrl:1
	s_nop 1
	v_add_f32_dpp v23, v23, v23 row_ror:2 row_mask:0xf bank_mask:0xf bound_ctrl:1
	s_nop 1
	v_add_f32_dpp v23, v23, v23 row_ror:1 row_mask:0xf bank_mask:0xf bound_ctrl:1
	v_mov_b32_e32 v22, v23
	s_nop 1
	v_permlane16_swap_b32_e32 v23, v22
	v_add_f32_e32 v23, v23, v22
	v_mov_b32_e32 v22, v23
	s_nop 1
	v_permlane32_swap_b32_e32 v23, v22
	v_add_f32_e32 v23, v23, v22
	s_and_saveexec_b64 s[12:13], s[6:7]
	v_mov_b32_e32 v5, v23
	v_fmamk_f32 v5, v5, 0x3a800000, v112
	v_mul_f32_e32 v6, 0x4f800000, v5
	v_cmp_gt_f32_e32 vcc, s67, v5
	v_mul_f32_e32 v4, 0x3a800000, v4
	s_nop 0
	v_cndmask_b32_e32 v5, v5, v6, vcc
	v_sqrt_f32_e32 v6, v5
	s_nop 0
	v_add_u32_e32 v7, -1, v6
	v_fma_f32 v9, -v7, v6, v5
	v_add_u32_e32 v8, 1, v6
	v_cmp_ge_f32_e64 s[8:9], 0, v9
	s_nop 1
	v_cndmask_b32_e64 v7, v6, v7, s[8:9]
	v_fma_f32 v6, -v8, v6, v5
	v_cmp_lt_f32_e64 s[8:9], 0, v6
	s_nop 1
	v_cndmask_b32_e64 v6, v7, v8, s[8:9]
	v_mul_f32_e32 v7, 0x37800000, v6
	v_cndmask_b32_e32 v6, v6, v7, vcc
	v_cmp_class_f32_e32 vcc, v5, v113
	s_nop 1
	v_cndmask_b32_e32 v5, v6, v5, vcc
	v_div_scale_f32 v6, s[8:9], v5, v5, 1.0
	v_rcp_f32_e32 v7, v6
	s_nop 0
	v_fma_f32 v8, -v6, v7, 1.0
	v_fmac_f32_e32 v7, v8, v7
	v_div_scale_f32 v8, vcc, 1.0, v5, 1.0
	v_mul_f32_e32 v9, v8, v7
	v_fma_f32 v10, -v6, v9, v8
	v_fmac_f32_e32 v9, v10, v7
	v_fma_f32 v6, -v6, v9, v8
	s_nop 1
	v_div_fmas_f32 v6, v6, v7, v9
	v_div_fixup_f32 v5, v6, v5, 1.0
	ds_write_b64 v62, v[4:5]
	s_or_b64 exec, exec, s[12:13]
	s_waitcnt vmcnt(28)
	v_mov_b32_e32 v4, v36
	v_mov_b32_e32 v5, v37
	v_mov_b32_e32 v6, v38
	v_mov_b32_e32 v7, v39
	v_mov_b32_e32 v8, v40
	v_mov_b32_e32 v9, v41
	v_mov_b32_e32 v10, v42
	v_mov_b32_e32 v11, v43
	v_lshlrev_b32_e32 v13, 16, v4
	v_and_b32_e32 v14, 0xffff0000, v4
	v_lshlrev_b32_e32 v15, 16, v5
	v_and_b32_e32 v5, 0xffff0000, v5
	v_lshlrev_b32_e32 v16, 16, v6
	v_and_b32_e32 v6, 0xffff0000, v6
	v_lshlrev_b32_e32 v17, 16, v7
	v_and_b32_e32 v7, 0xffff0000, v7
	v_lshlrev_b32_e32 v18, 16, v8
	v_and_b32_e32 v8, 0xffff0000, v8
	v_lshlrev_b32_e32 v19, 16, v9
	v_and_b32_e32 v9, 0xffff0000, v9
	v_lshlrev_b32_e32 v20, 16, v10
	v_and_b32_e32 v10, 0xffff0000, v10
	v_lshlrev_b32_e32 v21, 16, v11
	v_and_b32_e32 v11, 0xffff0000, v11
	v_add_f32_e32 v22, v13, v14
	v_add_f32_e32 v23, v15, v5
	v_add_f32_e32 v24, v16, v6
	v_add_f32_e32 v25, v17, v7
	v_add_f32_e32 v26, v18, v8
	v_add_f32_e32 v27, v19, v9
	v_add_f32_e32 v12, v20, v10
	v_add_f32_e32 v4, v21, v11
	v_add_f32_e32 v22, v22, v23
	v_add_f32_e32 v24, v24, v25
	v_add_f32_e32 v26, v26, v27
	v_add_f32_e32 v4, v12, v4
	v_add_f32_e32 v22, v22, v24
	v_add_f32_e32 v4, v26, v4
	v_add_f32_e32 v4, v22, v4
	s_nop 1
	v_add_f32_dpp v4, v4, v4 row_ror:8 row_mask:0xf bank_mask:0xf bound_ctrl:1
	s_nop 1
	v_add_f32_dpp v4, v4, v4 row_ror:4 row_mask:0xf bank_mask:0xf bound_ctrl:1
	s_nop 1
	v_add_f32_dpp v4, v4, v4 row_ror:2 row_mask:0xf bank_mask:0xf bound_ctrl:1
	s_nop 1
	v_add_f32_dpp v4, v4, v4 row_ror:1 row_mask:0xf bank_mask:0xf bound_ctrl:1
	v_mov_b32_e32 v22, v4
	s_nop 1
	v_permlane16_swap_b32_e32 v4, v22
	v_add_f32_e32 v4, v4, v22
	v_mov_b32_e32 v22, v4
	s_nop 1
	v_permlane32_swap_b32_e32 v4, v22
	v_add_f32_e32 v4, v4, v22
	v_fmac_f32_e32 v13, 0xba800000, v4
	v_fmac_f32_e32 v14, 0xba800000, v4
	v_fmac_f32_e32 v15, 0xba800000, v4
	v_fmac_f32_e32 v5, 0xba800000, v4
	v_fmac_f32_e32 v16, 0xba800000, v4
	v_fmac_f32_e32 v6, 0xba800000, v4
	v_fmac_f32_e32 v17, 0xba800000, v4
	v_fmac_f32_e32 v7, 0xba800000, v4
	v_fmac_f32_e32 v18, 0xba800000, v4
	v_fmac_f32_e32 v8, 0xba800000, v4
	v_fmac_f32_e32 v19, 0xba800000, v4
	v_fmac_f32_e32 v9, 0xba800000, v4
	v_fmac_f32_e32 v20, 0xba800000, v4
	v_fmac_f32_e32 v10, 0xba800000, v4
	v_fmac_f32_e32 v21, 0xba800000, v4
	v_fmac_f32_e32 v11, 0xba800000, v4
	v_mul_f32_e32 v23, v13, v13
	v_fmac_f32_e32 v23, v14, v14
	v_fmac_f32_e32 v23, v15, v15
	v_fmac_f32_e32 v23, v5, v5
	v_fmac_f32_e32 v23, v16, v16
	v_fmac_f32_e32 v23, v6, v6
	v_fmac_f32_e32 v23, v17, v17
	v_fmac_f32_e32 v23, v7, v7
	v_fmac_f32_e32 v23, v18, v18
	v_fmac_f32_e32 v23, v8, v8
	v_fmac_f32_e32 v23, v19, v19
	v_fmac_f32_e32 v23, v9, v9
	v_fmac_f32_e32 v23, v20, v20
	v_fmac_f32_e32 v23, v10, v10
	v_fmac_f32_e32 v23, v21, v21
	v_fmac_f32_e32 v23, v11, v11
	s_nop 1
	v_add_f32_dpp v23, v23, v23 row_ror:8 row_mask:0xf bank_mask:0xf bound_ctrl:1
	s_nop 1
	v_add_f32_dpp v23, v23, v23 row_ror:4 row_mask:0xf bank_mask:0xf bound_ctrl:1
	s_nop 1
	v_add_f32_dpp v23, v23, v23 row_ror:2 row_mask:0xf bank_mask:0xf bound_ctrl:1
	s_nop 1
	v_add_f32_dpp v23, v23, v23 row_ror:1 row_mask:0xf bank_mask:0xf bound_ctrl:1
	v_mov_b32_e32 v22, v23
	s_nop 1
	v_permlane16_swap_b32_e32 v23, v22
	v_add_f32_e32 v23, v23, v22
	v_mov_b32_e32 v22, v23
	s_nop 1
	v_permlane32_swap_b32_e32 v23, v22
	v_add_f32_e32 v23, v23, v22
	s_and_saveexec_b64 s[12:13], s[6:7]
	v_mov_b32_e32 v5, v23
	v_fmamk_f32 v5, v5, 0x3a800000, v112
	v_mul_f32_e32 v6, 0x4f800000, v5
	v_cmp_gt_f32_e32 vcc, s67, v5
	v_mul_f32_e32 v4, 0x3a800000, v4
	s_nop 0
	v_cndmask_b32_e32 v5, v5, v6, vcc
	v_sqrt_f32_e32 v6, v5
	s_nop 0
	v_add_u32_e32 v7, -1, v6
	v_fma_f32 v9, -v7, v6, v5
	v_add_u32_e32 v8, 1, v6
	v_cmp_ge_f32_e64 s[8:9], 0, v9
	s_nop 1
	v_cndmask_b32_e64 v7, v6, v7, s[8:9]
	v_fma_f32 v6, -v8, v6, v5
	v_cmp_lt_f32_e64 s[8:9], 0, v6
	s_nop 1
	v_cndmask_b32_e64 v6, v7, v8, s[8:9]
	v_mul_f32_e32 v7, 0x37800000, v6
	v_cndmask_b32_e32 v6, v6, v7, vcc
	v_cmp_class_f32_e32 vcc, v5, v113
	s_nop 1
	v_cndmask_b32_e32 v5, v6, v5, vcc
	v_div_scale_f32 v6, s[8:9], v5, v5, 1.0
	v_rcp_f32_e32 v7, v6
	s_nop 0
	v_fma_f32 v8, -v6, v7, 1.0
	v_fmac_f32_e32 v7, v8, v7
	v_div_scale_f32 v8, vcc, 1.0, v5, 1.0
	v_mul_f32_e32 v9, v8, v7
	v_fma_f32 v10, -v6, v9, v8
	v_fmac_f32_e32 v9, v10, v7
	v_fma_f32 v6, -v6, v9, v8
	s_nop 1
	v_div_fmas_f32 v6, v6, v7, v9
	v_div_fixup_f32 v5, v6, v5, 1.0
	ds_write_b64 v62, v[4:5] offset:8
	s_or_b64 exec, exec, s[12:13]
	s_waitcnt vmcnt(26)
	v_mov_b32_e32 v4, v44
	v_mov_b32_e32 v5, v45
	v_mov_b32_e32 v6, v46
	v_mov_b32_e32 v7, v47
	v_mov_b32_e32 v8, v48
	v_mov_b32_e32 v9, v49
	v_mov_b32_e32 v10, v50
	v_mov_b32_e32 v11, v51
	v_lshlrev_b32_e32 v13, 16, v4
	v_and_b32_e32 v14, 0xffff0000, v4
	v_lshlrev_b32_e32 v15, 16, v5
	v_and_b32_e32 v5, 0xffff0000, v5
	v_lshlrev_b32_e32 v16, 16, v6
	v_and_b32_e32 v6, 0xffff0000, v6
	v_lshlrev_b32_e32 v17, 16, v7
	v_and_b32_e32 v7, 0xffff0000, v7
	v_lshlrev_b32_e32 v18, 16, v8
	v_and_b32_e32 v8, 0xffff0000, v8
	v_lshlrev_b32_e32 v19, 16, v9
	v_and_b32_e32 v9, 0xffff0000, v9
	v_lshlrev_b32_e32 v20, 16, v10
	v_and_b32_e32 v10, 0xffff0000, v10
	v_lshlrev_b32_e32 v21, 16, v11
	v_and_b32_e32 v11, 0xffff0000, v11
	v_add_f32_e32 v22, v13, v14
	v_add_f32_e32 v23, v15, v5
	v_add_f32_e32 v24, v16, v6
	v_add_f32_e32 v25, v17, v7
	v_add_f32_e32 v26, v18, v8
	v_add_f32_e32 v27, v19, v9
	v_add_f32_e32 v12, v20, v10
	v_add_f32_e32 v4, v21, v11
	v_add_f32_e32 v22, v22, v23
	v_add_f32_e32 v24, v24, v25
	v_add_f32_e32 v26, v26, v27
	v_add_f32_e32 v4, v12, v4
	v_add_f32_e32 v22, v22, v24
	v_add_f32_e32 v4, v26, v4
	v_add_f32_e32 v4, v22, v4
	s_nop 1
	v_add_f32_dpp v4, v4, v4 row_ror:8 row_mask:0xf bank_mask:0xf bound_ctrl:1
	s_nop 1
	v_add_f32_dpp v4, v4, v4 row_ror:4 row_mask:0xf bank_mask:0xf bound_ctrl:1
	s_nop 1
	v_add_f32_dpp v4, v4, v4 row_ror:2 row_mask:0xf bank_mask:0xf bound_ctrl:1
	s_nop 1
	v_add_f32_dpp v4, v4, v4 row_ror:1 row_mask:0xf bank_mask:0xf bound_ctrl:1
	v_mov_b32_e32 v22, v4
	s_nop 1
	v_permlane16_swap_b32_e32 v4, v22
	v_add_f32_e32 v4, v4, v22
	v_mov_b32_e32 v22, v4
	s_nop 1
	v_permlane32_swap_b32_e32 v4, v22
	v_add_f32_e32 v4, v4, v22
	v_fmac_f32_e32 v13, 0xba800000, v4
	v_fmac_f32_e32 v14, 0xba800000, v4
	v_fmac_f32_e32 v15, 0xba800000, v4
	v_fmac_f32_e32 v5, 0xba800000, v4
	v_fmac_f32_e32 v16, 0xba800000, v4
	v_fmac_f32_e32 v6, 0xba800000, v4
	v_fmac_f32_e32 v17, 0xba800000, v4
	v_fmac_f32_e32 v7, 0xba800000, v4
	v_fmac_f32_e32 v18, 0xba800000, v4
	v_fmac_f32_e32 v8, 0xba800000, v4
	v_fmac_f32_e32 v19, 0xba800000, v4
	v_fmac_f32_e32 v9, 0xba800000, v4
	v_fmac_f32_e32 v20, 0xba800000, v4
	v_fmac_f32_e32 v10, 0xba800000, v4
	v_fmac_f32_e32 v21, 0xba800000, v4
	v_fmac_f32_e32 v11, 0xba800000, v4
	v_mul_f32_e32 v23, v13, v13
	v_fmac_f32_e32 v23, v14, v14
	v_fmac_f32_e32 v23, v15, v15
	v_fmac_f32_e32 v23, v5, v5
	v_fmac_f32_e32 v23, v16, v16
	v_fmac_f32_e32 v23, v6, v6
	v_fmac_f32_e32 v23, v17, v17
	v_fmac_f32_e32 v23, v7, v7
	v_fmac_f32_e32 v23, v18, v18
	v_fmac_f32_e32 v23, v8, v8
	v_fmac_f32_e32 v23, v19, v19
	v_fmac_f32_e32 v23, v9, v9
	v_fmac_f32_e32 v23, v20, v20
	v_fmac_f32_e32 v23, v10, v10
	v_fmac_f32_e32 v23, v21, v21
	v_fmac_f32_e32 v23, v11, v11
	s_nop 1
	v_add_f32_dpp v23, v23, v23 row_ror:8 row_mask:0xf bank_mask:0xf bound_ctrl:1
	s_nop 1
	v_add_f32_dpp v23, v23, v23 row_ror:4 row_mask:0xf bank_mask:0xf bound_ctrl:1
	s_nop 1
	v_add_f32_dpp v23, v23, v23 row_ror:2 row_mask:0xf bank_mask:0xf bound_ctrl:1
	s_nop 1
	v_add_f32_dpp v23, v23, v23 row_ror:1 row_mask:0xf bank_mask:0xf bound_ctrl:1
	v_mov_b32_e32 v22, v23
	s_nop 1
	v_permlane16_swap_b32_e32 v23, v22
	v_add_f32_e32 v23, v23, v22
	v_mov_b32_e32 v22, v23
	s_nop 1
	v_permlane32_swap_b32_e32 v23, v22
	v_add_f32_e32 v23, v23, v22
	s_and_saveexec_b64 s[12:13], s[6:7]
	v_mov_b32_e32 v5, v23
	v_fmamk_f32 v5, v5, 0x3a800000, v112
	v_mul_f32_e32 v6, 0x4f800000, v5
	v_cmp_gt_f32_e32 vcc, s67, v5
	v_mul_f32_e32 v4, 0x3a800000, v4
	s_nop 0
	v_cndmask_b32_e32 v5, v5, v6, vcc
	v_sqrt_f32_e32 v6, v5
	s_nop 0
	v_add_u32_e32 v7, -1, v6
	v_fma_f32 v9, -v7, v6, v5
	v_add_u32_e32 v8, 1, v6
	v_cmp_ge_f32_e64 s[8:9], 0, v9
	s_nop 1
	v_cndmask_b32_e64 v7, v6, v7, s[8:9]
	v_fma_f32 v6, -v8, v6, v5
	v_cmp_lt_f32_e64 s[8:9], 0, v6
	s_nop 1
	v_cndmask_b32_e64 v6, v7, v8, s[8:9]
	v_mul_f32_e32 v7, 0x37800000, v6
	v_cndmask_b32_e32 v6, v6, v7, vcc
	v_cmp_class_f32_e32 vcc, v5, v113
	s_nop 1
	v_cndmask_b32_e32 v5, v6, v5, vcc
	v_div_scale_f32 v6, s[8:9], v5, v5, 1.0
	v_rcp_f32_e32 v7, v6
	s_nop 0
	v_fma_f32 v8, -v6, v7, 1.0
	v_fmac_f32_e32 v7, v8, v7
	v_div_scale_f32 v8, vcc, 1.0, v5, 1.0
	v_mul_f32_e32 v9, v8, v7
	v_fma_f32 v10, -v6, v9, v8
	v_fmac_f32_e32 v9, v10, v7
	v_fma_f32 v6, -v6, v9, v8
	s_nop 1
	v_div_fmas_f32 v6, v6, v7, v9
	v_div_fixup_f32 v5, v6, v5, 1.0
	ds_write_b64 v62, v[4:5] offset:16
	s_or_b64 exec, exec, s[12:13]
	s_waitcnt vmcnt(24)
	v_mov_b32_e32 v4, v52
	v_mov_b32_e32 v5, v53
	v_mov_b32_e32 v6, v54
	v_mov_b32_e32 v7, v55
	v_mov_b32_e32 v8, v56
	v_mov_b32_e32 v9, v57
	v_mov_b32_e32 v10, v58
	v_mov_b32_e32 v11, v59
	v_lshlrev_b32_e32 v13, 16, v4
	v_and_b32_e32 v14, 0xffff0000, v4
	v_lshlrev_b32_e32 v15, 16, v5
	v_and_b32_e32 v5, 0xffff0000, v5
	v_lshlrev_b32_e32 v16, 16, v6
	v_and_b32_e32 v6, 0xffff0000, v6
	v_lshlrev_b32_e32 v17, 16, v7
	v_and_b32_e32 v7, 0xffff0000, v7
	v_lshlrev_b32_e32 v18, 16, v8
	v_and_b32_e32 v8, 0xffff0000, v8
	v_lshlrev_b32_e32 v19, 16, v9
	v_and_b32_e32 v9, 0xffff0000, v9
	v_lshlrev_b32_e32 v20, 16, v10
	v_and_b32_e32 v10, 0xffff0000, v10
	v_lshlrev_b32_e32 v21, 16, v11
	v_and_b32_e32 v11, 0xffff0000, v11
	v_add_f32_e32 v22, v13, v14
	v_add_f32_e32 v23, v15, v5
	v_add_f32_e32 v24, v16, v6
	v_add_f32_e32 v25, v17, v7
	v_add_f32_e32 v26, v18, v8
	v_add_f32_e32 v27, v19, v9
	v_add_f32_e32 v12, v20, v10
	v_add_f32_e32 v4, v21, v11
	v_add_f32_e32 v22, v22, v23
	v_add_f32_e32 v24, v24, v25
	v_add_f32_e32 v26, v26, v27
	v_add_f32_e32 v4, v12, v4
	v_add_f32_e32 v22, v22, v24
	v_add_f32_e32 v4, v26, v4
	v_add_f32_e32 v4, v22, v4
	s_nop 1
	v_add_f32_dpp v4, v4, v4 row_ror:8 row_mask:0xf bank_mask:0xf bound_ctrl:1
	s_nop 1
	v_add_f32_dpp v4, v4, v4 row_ror:4 row_mask:0xf bank_mask:0xf bound_ctrl:1
	s_nop 1
	v_add_f32_dpp v4, v4, v4 row_ror:2 row_mask:0xf bank_mask:0xf bound_ctrl:1
	s_nop 1
	v_add_f32_dpp v4, v4, v4 row_ror:1 row_mask:0xf bank_mask:0xf bound_ctrl:1
	v_mov_b32_e32 v22, v4
	s_nop 1
	v_permlane16_swap_b32_e32 v4, v22
	v_add_f32_e32 v4, v4, v22
	v_mov_b32_e32 v22, v4
	s_nop 1
	v_permlane32_swap_b32_e32 v4, v22
	v_add_f32_e32 v4, v4, v22
	v_fmac_f32_e32 v13, 0xba800000, v4
	v_fmac_f32_e32 v14, 0xba800000, v4
	v_fmac_f32_e32 v15, 0xba800000, v4
	v_fmac_f32_e32 v5, 0xba800000, v4
	v_fmac_f32_e32 v16, 0xba800000, v4
	v_fmac_f32_e32 v6, 0xba800000, v4
	v_fmac_f32_e32 v17, 0xba800000, v4
	v_fmac_f32_e32 v7, 0xba800000, v4
	v_fmac_f32_e32 v18, 0xba800000, v4
	v_fmac_f32_e32 v8, 0xba800000, v4
	v_fmac_f32_e32 v19, 0xba800000, v4
	v_fmac_f32_e32 v9, 0xba800000, v4
	v_fmac_f32_e32 v20, 0xba800000, v4
	v_fmac_f32_e32 v10, 0xba800000, v4
	v_fmac_f32_e32 v21, 0xba800000, v4
	v_fmac_f32_e32 v11, 0xba800000, v4
	v_mul_f32_e32 v23, v13, v13
	v_fmac_f32_e32 v23, v14, v14
	v_fmac_f32_e32 v23, v15, v15
	v_fmac_f32_e32 v23, v5, v5
	v_fmac_f32_e32 v23, v16, v16
	v_fmac_f32_e32 v23, v6, v6
	v_fmac_f32_e32 v23, v17, v17
	v_fmac_f32_e32 v23, v7, v7
	v_fmac_f32_e32 v23, v18, v18
	v_fmac_f32_e32 v23, v8, v8
	v_fmac_f32_e32 v23, v19, v19
	v_fmac_f32_e32 v23, v9, v9
	v_fmac_f32_e32 v23, v20, v20
	v_fmac_f32_e32 v23, v10, v10
	v_fmac_f32_e32 v23, v21, v21
	v_fmac_f32_e32 v23, v11, v11
	s_nop 1
	v_add_f32_dpp v23, v23, v23 row_ror:8 row_mask:0xf bank_mask:0xf bound_ctrl:1
	s_nop 1
	v_add_f32_dpp v23, v23, v23 row_ror:4 row_mask:0xf bank_mask:0xf bound_ctrl:1
	s_nop 1
	v_add_f32_dpp v23, v23, v23 row_ror:2 row_mask:0xf bank_mask:0xf bound_ctrl:1
	s_nop 1
	v_add_f32_dpp v23, v23, v23 row_ror:1 row_mask:0xf bank_mask:0xf bound_ctrl:1
	v_mov_b32_e32 v22, v23
	s_nop 1
	v_permlane16_swap_b32_e32 v23, v22
	v_add_f32_e32 v23, v23, v22
	v_mov_b32_e32 v22, v23
	s_nop 1
	v_permlane32_swap_b32_e32 v23, v22
	v_add_f32_e32 v23, v23, v22
	s_and_saveexec_b64 s[12:13], s[6:7]
	v_mov_b32_e32 v5, v23
	v_fmamk_f32 v5, v5, 0x3a800000, v112
	v_mul_f32_e32 v6, 0x4f800000, v5
	v_cmp_gt_f32_e32 vcc, s67, v5
	v_mul_f32_e32 v4, 0x3a800000, v4
	s_nop 0
	v_cndmask_b32_e32 v5, v5, v6, vcc
	v_sqrt_f32_e32 v6, v5
	s_nop 0
	v_add_u32_e32 v7, -1, v6
	v_fma_f32 v9, -v7, v6, v5
	v_add_u32_e32 v8, 1, v6
	v_cmp_ge_f32_e64 s[8:9], 0, v9
	s_nop 1
	v_cndmask_b32_e64 v7, v6, v7, s[8:9]
	v_fma_f32 v6, -v8, v6, v5
	v_cmp_lt_f32_e64 s[8:9], 0, v6
	s_nop 1
	v_cndmask_b32_e64 v6, v7, v8, s[8:9]
	v_mul_f32_e32 v7, 0x37800000, v6
	v_cndmask_b32_e32 v6, v6, v7, vcc
	v_cmp_class_f32_e32 vcc, v5, v113
	s_nop 1
	v_cndmask_b32_e32 v5, v6, v5, vcc
	v_div_scale_f32 v6, s[8:9], v5, v5, 1.0
	v_rcp_f32_e32 v7, v6
	s_nop 0
	v_fma_f32 v8, -v6, v7, 1.0
	v_fmac_f32_e32 v7, v8, v7
	v_div_scale_f32 v8, vcc, 1.0, v5, 1.0
	v_mul_f32_e32 v9, v8, v7
	v_fma_f32 v10, -v6, v9, v8
	v_fmac_f32_e32 v9, v10, v7
	v_fma_f32 v6, -v6, v9, v8
	s_nop 1
	v_div_fmas_f32 v6, v6, v7, v9
	v_div_fixup_f32 v5, v6, v5, 1.0
	ds_write_b64 v62, v[4:5] offset:24
	s_or_b64 exec, exec, s[12:13]
	s_waitcnt vmcnt(22)
	v_mov_b32_e32 v4, v66
	v_mov_b32_e32 v5, v67
	v_mov_b32_e32 v6, v68
	v_mov_b32_e32 v7, v69
	v_mov_b32_e32 v8, v70
	v_mov_b32_e32 v9, v71
	v_mov_b32_e32 v10, v72
	v_mov_b32_e32 v11, v73
	v_lshlrev_b32_e32 v13, 16, v4
	v_and_b32_e32 v14, 0xffff0000, v4
	v_lshlrev_b32_e32 v15, 16, v5
	v_and_b32_e32 v5, 0xffff0000, v5
	v_lshlrev_b32_e32 v16, 16, v6
	v_and_b32_e32 v6, 0xffff0000, v6
	v_lshlrev_b32_e32 v17, 16, v7
	v_and_b32_e32 v7, 0xffff0000, v7
	v_lshlrev_b32_e32 v18, 16, v8
	v_and_b32_e32 v8, 0xffff0000, v8
	v_lshlrev_b32_e32 v19, 16, v9
	v_and_b32_e32 v9, 0xffff0000, v9
	v_lshlrev_b32_e32 v20, 16, v10
	v_and_b32_e32 v10, 0xffff0000, v10
	v_lshlrev_b32_e32 v21, 16, v11
	v_and_b32_e32 v11, 0xffff0000, v11
	v_add_f32_e32 v22, v13, v14
	v_add_f32_e32 v23, v15, v5
	v_add_f32_e32 v24, v16, v6
	v_add_f32_e32 v25, v17, v7
	v_add_f32_e32 v26, v18, v8
	v_add_f32_e32 v27, v19, v9
	v_add_f32_e32 v12, v20, v10
	v_add_f32_e32 v4, v21, v11
	v_add_f32_e32 v22, v22, v23
	v_add_f32_e32 v24, v24, v25
	v_add_f32_e32 v26, v26, v27
	v_add_f32_e32 v4, v12, v4
	v_add_f32_e32 v22, v22, v24
	v_add_f32_e32 v4, v26, v4
	v_add_f32_e32 v4, v22, v4
	s_nop 1
	v_add_f32_dpp v4, v4, v4 row_ror:8 row_mask:0xf bank_mask:0xf bound_ctrl:1
	s_nop 1
	v_add_f32_dpp v4, v4, v4 row_ror:4 row_mask:0xf bank_mask:0xf bound_ctrl:1
	s_nop 1
	v_add_f32_dpp v4, v4, v4 row_ror:2 row_mask:0xf bank_mask:0xf bound_ctrl:1
	s_nop 1
	v_add_f32_dpp v4, v4, v4 row_ror:1 row_mask:0xf bank_mask:0xf bound_ctrl:1
	v_mov_b32_e32 v22, v4
	s_nop 1
	v_permlane16_swap_b32_e32 v4, v22
	v_add_f32_e32 v4, v4, v22
	v_mov_b32_e32 v22, v4
	s_nop 1
	v_permlane32_swap_b32_e32 v4, v22
	v_add_f32_e32 v4, v4, v22
	v_fmac_f32_e32 v13, 0xba800000, v4
	v_fmac_f32_e32 v14, 0xba800000, v4
	v_fmac_f32_e32 v15, 0xba800000, v4
	v_fmac_f32_e32 v5, 0xba800000, v4
	v_fmac_f32_e32 v16, 0xba800000, v4
	v_fmac_f32_e32 v6, 0xba800000, v4
	v_fmac_f32_e32 v17, 0xba800000, v4
	v_fmac_f32_e32 v7, 0xba800000, v4
	v_fmac_f32_e32 v18, 0xba800000, v4
	v_fmac_f32_e32 v8, 0xba800000, v4
	v_fmac_f32_e32 v19, 0xba800000, v4
	v_fmac_f32_e32 v9, 0xba800000, v4
	v_fmac_f32_e32 v20, 0xba800000, v4
	v_fmac_f32_e32 v10, 0xba800000, v4
	v_fmac_f32_e32 v21, 0xba800000, v4
	v_fmac_f32_e32 v11, 0xba800000, v4
	v_mul_f32_e32 v23, v13, v13
	v_fmac_f32_e32 v23, v14, v14
	v_fmac_f32_e32 v23, v15, v15
	v_fmac_f32_e32 v23, v5, v5
	v_fmac_f32_e32 v23, v16, v16
	v_fmac_f32_e32 v23, v6, v6
	v_fmac_f32_e32 v23, v17, v17
	v_fmac_f32_e32 v23, v7, v7
	v_fmac_f32_e32 v23, v18, v18
	v_fmac_f32_e32 v23, v8, v8
	v_fmac_f32_e32 v23, v19, v19
	v_fmac_f32_e32 v23, v9, v9
	v_fmac_f32_e32 v23, v20, v20
	v_fmac_f32_e32 v23, v10, v10
	v_fmac_f32_e32 v23, v21, v21
	v_fmac_f32_e32 v23, v11, v11
	s_nop 1
	v_add_f32_dpp v23, v23, v23 row_ror:8 row_mask:0xf bank_mask:0xf bound_ctrl:1
	s_nop 1
	v_add_f32_dpp v23, v23, v23 row_ror:4 row_mask:0xf bank_mask:0xf bound_ctrl:1
	s_nop 1
	v_add_f32_dpp v23, v23, v23 row_ror:2 row_mask:0xf bank_mask:0xf bound_ctrl:1
	s_nop 1
	v_add_f32_dpp v23, v23, v23 row_ror:1 row_mask:0xf bank_mask:0xf bound_ctrl:1
	v_mov_b32_e32 v22, v23
	s_nop 1
	v_permlane16_swap_b32_e32 v23, v22
	v_add_f32_e32 v23, v23, v22
	v_mov_b32_e32 v22, v23
	s_nop 1
	v_permlane32_swap_b32_e32 v23, v22
	v_add_f32_e32 v23, v23, v22
	s_and_saveexec_b64 s[12:13], s[6:7]
	v_mov_b32_e32 v5, v23
	v_fmamk_f32 v5, v5, 0x3a800000, v112
	v_mul_f32_e32 v6, 0x4f800000, v5
	v_cmp_gt_f32_e32 vcc, s67, v5
	v_mul_f32_e32 v4, 0x3a800000, v4
	s_nop 0
	v_cndmask_b32_e32 v5, v5, v6, vcc
	v_sqrt_f32_e32 v6, v5
	s_nop 0
	v_add_u32_e32 v7, -1, v6
	v_fma_f32 v9, -v7, v6, v5
	v_add_u32_e32 v8, 1, v6
	v_cmp_ge_f32_e64 s[8:9], 0, v9
	s_nop 1
	v_cndmask_b32_e64 v7, v6, v7, s[8:9]
	v_fma_f32 v6, -v8, v6, v5
	v_cmp_lt_f32_e64 s[8:9], 0, v6
	s_nop 1
	v_cndmask_b32_e64 v6, v7, v8, s[8:9]
	v_mul_f32_e32 v7, 0x37800000, v6
	v_cndmask_b32_e32 v6, v6, v7, vcc
	v_cmp_class_f32_e32 vcc, v5, v113
	s_nop 1
	v_cndmask_b32_e32 v5, v6, v5, vcc
	v_div_scale_f32 v6, s[8:9], v5, v5, 1.0
	v_rcp_f32_e32 v7, v6
	s_nop 0
	v_fma_f32 v8, -v6, v7, 1.0
	v_fmac_f32_e32 v7, v8, v7
	v_div_scale_f32 v8, vcc, 1.0, v5, 1.0
	v_mul_f32_e32 v9, v8, v7
	v_fma_f32 v10, -v6, v9, v8
	v_fmac_f32_e32 v9, v10, v7
	v_fma_f32 v6, -v6, v9, v8
	s_nop 1
	v_div_fmas_f32 v6, v6, v7, v9
	v_div_fixup_f32 v5, v6, v5, 1.0
	ds_write_b64 v62, v[4:5] offset:32
	s_or_b64 exec, exec, s[12:13]
	s_waitcnt vmcnt(20)
	v_mov_b32_e32 v4, v74
	v_mov_b32_e32 v5, v75
	v_mov_b32_e32 v6, v76
	v_mov_b32_e32 v7, v77
	v_mov_b32_e32 v8, v78
	v_mov_b32_e32 v9, v79
	v_mov_b32_e32 v10, v80
	v_mov_b32_e32 v11, v81
	v_lshlrev_b32_e32 v13, 16, v4
	v_and_b32_e32 v14, 0xffff0000, v4
	v_lshlrev_b32_e32 v15, 16, v5
	v_and_b32_e32 v5, 0xffff0000, v5
	v_lshlrev_b32_e32 v16, 16, v6
	v_and_b32_e32 v6, 0xffff0000, v6
	v_lshlrev_b32_e32 v17, 16, v7
	v_and_b32_e32 v7, 0xffff0000, v7
	v_lshlrev_b32_e32 v18, 16, v8
	v_and_b32_e32 v8, 0xffff0000, v8
	v_lshlrev_b32_e32 v19, 16, v9
	v_and_b32_e32 v9, 0xffff0000, v9
	v_lshlrev_b32_e32 v20, 16, v10
	v_and_b32_e32 v10, 0xffff0000, v10
	v_lshlrev_b32_e32 v21, 16, v11
	v_and_b32_e32 v11, 0xffff0000, v11
	v_add_f32_e32 v22, v13, v14
	v_add_f32_e32 v23, v15, v5
	v_add_f32_e32 v24, v16, v6
	v_add_f32_e32 v25, v17, v7
	v_add_f32_e32 v26, v18, v8
	v_add_f32_e32 v27, v19, v9
	v_add_f32_e32 v12, v20, v10
	v_add_f32_e32 v4, v21, v11
	v_add_f32_e32 v22, v22, v23
	v_add_f32_e32 v24, v24, v25
	v_add_f32_e32 v26, v26, v27
	v_add_f32_e32 v4, v12, v4
	v_add_f32_e32 v22, v22, v24
	v_add_f32_e32 v4, v26, v4
	v_add_f32_e32 v4, v22, v4
	s_nop 1
	v_add_f32_dpp v4, v4, v4 row_ror:8 row_mask:0xf bank_mask:0xf bound_ctrl:1
	s_nop 1
	v_add_f32_dpp v4, v4, v4 row_ror:4 row_mask:0xf bank_mask:0xf bound_ctrl:1
	s_nop 1
	v_add_f32_dpp v4, v4, v4 row_ror:2 row_mask:0xf bank_mask:0xf bound_ctrl:1
	s_nop 1
	v_add_f32_dpp v4, v4, v4 row_ror:1 row_mask:0xf bank_mask:0xf bound_ctrl:1
	v_mov_b32_e32 v22, v4
	s_nop 1
	v_permlane16_swap_b32_e32 v4, v22
	v_add_f32_e32 v4, v4, v22
	v_mov_b32_e32 v22, v4
	s_nop 1
	v_permlane32_swap_b32_e32 v4, v22
	v_add_f32_e32 v4, v4, v22
	v_fmac_f32_e32 v13, 0xba800000, v4
	v_fmac_f32_e32 v14, 0xba800000, v4
	v_fmac_f32_e32 v15, 0xba800000, v4
	v_fmac_f32_e32 v5, 0xba800000, v4
	v_fmac_f32_e32 v16, 0xba800000, v4
	v_fmac_f32_e32 v6, 0xba800000, v4
	v_fmac_f32_e32 v17, 0xba800000, v4
	v_fmac_f32_e32 v7, 0xba800000, v4
	v_fmac_f32_e32 v18, 0xba800000, v4
	v_fmac_f32_e32 v8, 0xba800000, v4
	v_fmac_f32_e32 v19, 0xba800000, v4
	v_fmac_f32_e32 v9, 0xba800000, v4
	v_fmac_f32_e32 v20, 0xba800000, v4
	v_fmac_f32_e32 v10, 0xba800000, v4
	v_fmac_f32_e32 v21, 0xba800000, v4
	v_fmac_f32_e32 v11, 0xba800000, v4
	v_mul_f32_e32 v23, v13, v13
	v_fmac_f32_e32 v23, v14, v14
	v_fmac_f32_e32 v23, v15, v15
	v_fmac_f32_e32 v23, v5, v5
	v_fmac_f32_e32 v23, v16, v16
	v_fmac_f32_e32 v23, v6, v6
	v_fmac_f32_e32 v23, v17, v17
	v_fmac_f32_e32 v23, v7, v7
	v_fmac_f32_e32 v23, v18, v18
	v_fmac_f32_e32 v23, v8, v8
	v_fmac_f32_e32 v23, v19, v19
	v_fmac_f32_e32 v23, v9, v9
	v_fmac_f32_e32 v23, v20, v20
	v_fmac_f32_e32 v23, v10, v10
	v_fmac_f32_e32 v23, v21, v21
	v_fmac_f32_e32 v23, v11, v11
	s_nop 1
	v_add_f32_dpp v23, v23, v23 row_ror:8 row_mask:0xf bank_mask:0xf bound_ctrl:1
	s_nop 1
	v_add_f32_dpp v23, v23, v23 row_ror:4 row_mask:0xf bank_mask:0xf bound_ctrl:1
	s_nop 1
	v_add_f32_dpp v23, v23, v23 row_ror:2 row_mask:0xf bank_mask:0xf bound_ctrl:1
	s_nop 1
	v_add_f32_dpp v23, v23, v23 row_ror:1 row_mask:0xf bank_mask:0xf bound_ctrl:1
	v_mov_b32_e32 v22, v23
	s_nop 1
	v_permlane16_swap_b32_e32 v23, v22
	v_add_f32_e32 v23, v23, v22
	v_mov_b32_e32 v22, v23
	s_nop 1
	v_permlane32_swap_b32_e32 v23, v22
	v_add_f32_e32 v23, v23, v22
	s_and_saveexec_b64 s[12:13], s[6:7]
	v_mov_b32_e32 v5, v23
	v_fmamk_f32 v5, v5, 0x3a800000, v112
	v_mul_f32_e32 v6, 0x4f800000, v5
	v_cmp_gt_f32_e32 vcc, s67, v5
	v_mul_f32_e32 v4, 0x3a800000, v4
	s_nop 0
	v_cndmask_b32_e32 v5, v5, v6, vcc
	v_sqrt_f32_e32 v6, v5
	s_nop 0
	v_add_u32_e32 v7, -1, v6
	v_fma_f32 v9, -v7, v6, v5
	v_add_u32_e32 v8, 1, v6
	v_cmp_ge_f32_e64 s[8:9], 0, v9
	s_nop 1
	v_cndmask_b32_e64 v7, v6, v7, s[8:9]
	v_fma_f32 v6, -v8, v6, v5
	v_cmp_lt_f32_e64 s[8:9], 0, v6
	s_nop 1
	v_cndmask_b32_e64 v6, v7, v8, s[8:9]
	v_mul_f32_e32 v7, 0x37800000, v6
	v_cndmask_b32_e32 v6, v6, v7, vcc
	v_cmp_class_f32_e32 vcc, v5, v113
	s_nop 1
	v_cndmask_b32_e32 v5, v6, v5, vcc
	v_div_scale_f32 v6, s[8:9], v5, v5, 1.0
	v_rcp_f32_e32 v7, v6
	s_nop 0
	v_fma_f32 v8, -v6, v7, 1.0
	v_fmac_f32_e32 v7, v8, v7
	v_div_scale_f32 v8, vcc, 1.0, v5, 1.0
	v_mul_f32_e32 v9, v8, v7
	v_fma_f32 v10, -v6, v9, v8
	v_fmac_f32_e32 v9, v10, v7
	v_fma_f32 v6, -v6, v9, v8
	s_nop 1
	v_div_fmas_f32 v6, v6, v7, v9
	v_div_fixup_f32 v5, v6, v5, 1.0
	ds_write_b64 v62, v[4:5] offset:40
	s_or_b64 exec, exec, s[12:13]
	s_waitcnt vmcnt(18)
	v_mov_b32_e32 v4, v82
	v_mov_b32_e32 v5, v83
	v_mov_b32_e32 v6, v84
	v_mov_b32_e32 v7, v85
	v_mov_b32_e32 v8, v86
	v_mov_b32_e32 v9, v87
	v_mov_b32_e32 v10, v88
	v_mov_b32_e32 v11, v89
	v_lshlrev_b32_e32 v13, 16, v4
	v_and_b32_e32 v14, 0xffff0000, v4
	v_lshlrev_b32_e32 v15, 16, v5
	v_and_b32_e32 v5, 0xffff0000, v5
	v_lshlrev_b32_e32 v16, 16, v6
	v_and_b32_e32 v6, 0xffff0000, v6
	v_lshlrev_b32_e32 v17, 16, v7
	v_and_b32_e32 v7, 0xffff0000, v7
	v_lshlrev_b32_e32 v18, 16, v8
	v_and_b32_e32 v8, 0xffff0000, v8
	v_lshlrev_b32_e32 v19, 16, v9
	v_and_b32_e32 v9, 0xffff0000, v9
	v_lshlrev_b32_e32 v20, 16, v10
	v_and_b32_e32 v10, 0xffff0000, v10
	v_lshlrev_b32_e32 v21, 16, v11
	v_and_b32_e32 v11, 0xffff0000, v11
	v_add_f32_e32 v22, v13, v14
	v_add_f32_e32 v23, v15, v5
	v_add_f32_e32 v24, v16, v6
	v_add_f32_e32 v25, v17, v7
	v_add_f32_e32 v26, v18, v8
	v_add_f32_e32 v27, v19, v9
	v_add_f32_e32 v12, v20, v10
	v_add_f32_e32 v4, v21, v11
	v_add_f32_e32 v22, v22, v23
	v_add_f32_e32 v24, v24, v25
	v_add_f32_e32 v26, v26, v27
	v_add_f32_e32 v4, v12, v4
	v_add_f32_e32 v22, v22, v24
	v_add_f32_e32 v4, v26, v4
	v_add_f32_e32 v4, v22, v4
	s_nop 1
	v_add_f32_dpp v4, v4, v4 row_ror:8 row_mask:0xf bank_mask:0xf bound_ctrl:1
	s_nop 1
	v_add_f32_dpp v4, v4, v4 row_ror:4 row_mask:0xf bank_mask:0xf bound_ctrl:1
	s_nop 1
	v_add_f32_dpp v4, v4, v4 row_ror:2 row_mask:0xf bank_mask:0xf bound_ctrl:1
	s_nop 1
	v_add_f32_dpp v4, v4, v4 row_ror:1 row_mask:0xf bank_mask:0xf bound_ctrl:1
	v_mov_b32_e32 v22, v4
	s_nop 1
	v_permlane16_swap_b32_e32 v4, v22
	v_add_f32_e32 v4, v4, v22
	v_mov_b32_e32 v22, v4
	s_nop 1
	v_permlane32_swap_b32_e32 v4, v22
	v_add_f32_e32 v4, v4, v22
	v_fmac_f32_e32 v13, 0xba800000, v4
	v_fmac_f32_e32 v14, 0xba800000, v4
	v_fmac_f32_e32 v15, 0xba800000, v4
	v_fmac_f32_e32 v5, 0xba800000, v4
	v_fmac_f32_e32 v16, 0xba800000, v4
	v_fmac_f32_e32 v6, 0xba800000, v4
	v_fmac_f32_e32 v17, 0xba800000, v4
	v_fmac_f32_e32 v7, 0xba800000, v4
	v_fmac_f32_e32 v18, 0xba800000, v4
	v_fmac_f32_e32 v8, 0xba800000, v4
	v_fmac_f32_e32 v19, 0xba800000, v4
	v_fmac_f32_e32 v9, 0xba800000, v4
	v_fmac_f32_e32 v20, 0xba800000, v4
	v_fmac_f32_e32 v10, 0xba800000, v4
	v_fmac_f32_e32 v21, 0xba800000, v4
	v_fmac_f32_e32 v11, 0xba800000, v4
	v_mul_f32_e32 v23, v13, v13
	v_fmac_f32_e32 v23, v14, v14
	v_fmac_f32_e32 v23, v15, v15
	v_fmac_f32_e32 v23, v5, v5
	v_fmac_f32_e32 v23, v16, v16
	v_fmac_f32_e32 v23, v6, v6
	v_fmac_f32_e32 v23, v17, v17
	v_fmac_f32_e32 v23, v7, v7
	v_fmac_f32_e32 v23, v18, v18
	v_fmac_f32_e32 v23, v8, v8
	v_fmac_f32_e32 v23, v19, v19
	v_fmac_f32_e32 v23, v9, v9
	v_fmac_f32_e32 v23, v20, v20
	v_fmac_f32_e32 v23, v10, v10
	v_fmac_f32_e32 v23, v21, v21
	v_fmac_f32_e32 v23, v11, v11
	s_nop 1
	v_add_f32_dpp v23, v23, v23 row_ror:8 row_mask:0xf bank_mask:0xf bound_ctrl:1
	s_nop 1
	v_add_f32_dpp v23, v23, v23 row_ror:4 row_mask:0xf bank_mask:0xf bound_ctrl:1
	s_nop 1
	v_add_f32_dpp v23, v23, v23 row_ror:2 row_mask:0xf bank_mask:0xf bound_ctrl:1
	s_nop 1
	v_add_f32_dpp v23, v23, v23 row_ror:1 row_mask:0xf bank_mask:0xf bound_ctrl:1
	v_mov_b32_e32 v22, v23
	s_nop 1
	v_permlane16_swap_b32_e32 v23, v22
	v_add_f32_e32 v23, v23, v22
	v_mov_b32_e32 v22, v23
	s_nop 1
	v_permlane32_swap_b32_e32 v23, v22
	v_add_f32_e32 v23, v23, v22
	s_and_saveexec_b64 s[12:13], s[6:7]
	v_mov_b32_e32 v5, v23
	v_fmamk_f32 v5, v5, 0x3a800000, v112
	v_mul_f32_e32 v6, 0x4f800000, v5
	v_cmp_gt_f32_e32 vcc, s67, v5
	v_mul_f32_e32 v4, 0x3a800000, v4
	s_nop 0
	v_cndmask_b32_e32 v5, v5, v6, vcc
	v_sqrt_f32_e32 v6, v5
	s_nop 0
	v_add_u32_e32 v7, -1, v6
	v_fma_f32 v9, -v7, v6, v5
	v_add_u32_e32 v8, 1, v6
	v_cmp_ge_f32_e64 s[8:9], 0, v9
	s_nop 1
	v_cndmask_b32_e64 v7, v6, v7, s[8:9]
	v_fma_f32 v6, -v8, v6, v5
	v_cmp_lt_f32_e64 s[8:9], 0, v6
	s_nop 1
	v_cndmask_b32_e64 v6, v7, v8, s[8:9]
	v_mul_f32_e32 v7, 0x37800000, v6
	v_cndmask_b32_e32 v6, v6, v7, vcc
	v_cmp_class_f32_e32 vcc, v5, v113
	s_nop 1
	v_cndmask_b32_e32 v5, v6, v5, vcc
	v_div_scale_f32 v6, s[8:9], v5, v5, 1.0
	v_rcp_f32_e32 v7, v6
	s_nop 0
	v_fma_f32 v8, -v6, v7, 1.0
	v_fmac_f32_e32 v7, v8, v7
	v_div_scale_f32 v8, vcc, 1.0, v5, 1.0
	v_mul_f32_e32 v9, v8, v7
	v_fma_f32 v10, -v6, v9, v8
	v_fmac_f32_e32 v9, v10, v7
	v_fma_f32 v6, -v6, v9, v8
	s_nop 1
	v_div_fmas_f32 v6, v6, v7, v9
	v_div_fixup_f32 v5, v6, v5, 1.0
	ds_write_b64 v62, v[4:5] offset:48
	s_or_b64 exec, exec, s[12:13]
	s_waitcnt vmcnt(16)
	v_mov_b32_e32 v4, v90
	v_mov_b32_e32 v5, v91
	v_mov_b32_e32 v6, v92
	v_mov_b32_e32 v7, v93
	v_mov_b32_e32 v8, v94
	v_mov_b32_e32 v9, v95
	v_mov_b32_e32 v10, v96
	v_mov_b32_e32 v11, v97
	v_lshlrev_b32_e32 v13, 16, v4
	v_and_b32_e32 v14, 0xffff0000, v4
	v_lshlrev_b32_e32 v15, 16, v5
	v_and_b32_e32 v5, 0xffff0000, v5
	v_lshlrev_b32_e32 v16, 16, v6
	v_and_b32_e32 v6, 0xffff0000, v6
	v_lshlrev_b32_e32 v17, 16, v7
	v_and_b32_e32 v7, 0xffff0000, v7
	v_lshlrev_b32_e32 v18, 16, v8
	v_and_b32_e32 v8, 0xffff0000, v8
	v_lshlrev_b32_e32 v19, 16, v9
	v_and_b32_e32 v9, 0xffff0000, v9
	v_lshlrev_b32_e32 v20, 16, v10
	v_and_b32_e32 v10, 0xffff0000, v10
	v_lshlrev_b32_e32 v21, 16, v11
	v_and_b32_e32 v11, 0xffff0000, v11
	v_add_f32_e32 v22, v13, v14
	v_add_f32_e32 v23, v15, v5
	v_add_f32_e32 v24, v16, v6
	v_add_f32_e32 v25, v17, v7
	v_add_f32_e32 v26, v18, v8
	v_add_f32_e32 v27, v19, v9
	v_add_f32_e32 v12, v20, v10
	v_add_f32_e32 v4, v21, v11
	v_add_f32_e32 v22, v22, v23
	v_add_f32_e32 v24, v24, v25
	v_add_f32_e32 v26, v26, v27
	v_add_f32_e32 v4, v12, v4
	v_add_f32_e32 v22, v22, v24
	v_add_f32_e32 v4, v26, v4
	v_add_f32_e32 v4, v22, v4
	s_nop 1
	v_add_f32_dpp v4, v4, v4 row_ror:8 row_mask:0xf bank_mask:0xf bound_ctrl:1
	s_nop 1
	v_add_f32_dpp v4, v4, v4 row_ror:4 row_mask:0xf bank_mask:0xf bound_ctrl:1
	s_nop 1
	v_add_f32_dpp v4, v4, v4 row_ror:2 row_mask:0xf bank_mask:0xf bound_ctrl:1
	s_nop 1
	v_add_f32_dpp v4, v4, v4 row_ror:1 row_mask:0xf bank_mask:0xf bound_ctrl:1
	v_mov_b32_e32 v22, v4
	s_nop 1
	v_permlane16_swap_b32_e32 v4, v22
	v_add_f32_e32 v4, v4, v22
	v_mov_b32_e32 v22, v4
	s_nop 1
	v_permlane32_swap_b32_e32 v4, v22
	v_add_f32_e32 v4, v4, v22
	v_fmac_f32_e32 v13, 0xba800000, v4
	v_fmac_f32_e32 v14, 0xba800000, v4
	v_fmac_f32_e32 v15, 0xba800000, v4
	v_fmac_f32_e32 v5, 0xba800000, v4
	v_fmac_f32_e32 v16, 0xba800000, v4
	v_fmac_f32_e32 v6, 0xba800000, v4
	v_fmac_f32_e32 v17, 0xba800000, v4
	v_fmac_f32_e32 v7, 0xba800000, v4
	v_fmac_f32_e32 v18, 0xba800000, v4
	v_fmac_f32_e32 v8, 0xba800000, v4
	v_fmac_f32_e32 v19, 0xba800000, v4
	v_fmac_f32_e32 v9, 0xba800000, v4
	v_fmac_f32_e32 v20, 0xba800000, v4
	v_fmac_f32_e32 v10, 0xba800000, v4
	v_fmac_f32_e32 v21, 0xba800000, v4
	v_fmac_f32_e32 v11, 0xba800000, v4
	v_mul_f32_e32 v23, v13, v13
	v_fmac_f32_e32 v23, v14, v14
	v_fmac_f32_e32 v23, v15, v15
	v_fmac_f32_e32 v23, v5, v5
	v_fmac_f32_e32 v23, v16, v16
	v_fmac_f32_e32 v23, v6, v6
	v_fmac_f32_e32 v23, v17, v17
	v_fmac_f32_e32 v23, v7, v7
	v_fmac_f32_e32 v23, v18, v18
	v_fmac_f32_e32 v23, v8, v8
	v_fmac_f32_e32 v23, v19, v19
	v_fmac_f32_e32 v23, v9, v9
	v_fmac_f32_e32 v23, v20, v20
	v_fmac_f32_e32 v23, v10, v10
	v_fmac_f32_e32 v23, v21, v21
	v_fmac_f32_e32 v23, v11, v11
	s_nop 1
	v_add_f32_dpp v23, v23, v23 row_ror:8 row_mask:0xf bank_mask:0xf bound_ctrl:1
	s_nop 1
	v_add_f32_dpp v23, v23, v23 row_ror:4 row_mask:0xf bank_mask:0xf bound_ctrl:1
	s_nop 1
	v_add_f32_dpp v23, v23, v23 row_ror:2 row_mask:0xf bank_mask:0xf bound_ctrl:1
	s_nop 1
	v_add_f32_dpp v23, v23, v23 row_ror:1 row_mask:0xf bank_mask:0xf bound_ctrl:1
	v_mov_b32_e32 v22, v23
	s_nop 1
	v_permlane16_swap_b32_e32 v23, v22
	v_add_f32_e32 v23, v23, v22
	v_mov_b32_e32 v22, v23
	s_nop 1
	v_permlane32_swap_b32_e32 v23, v22
	v_add_f32_e32 v23, v23, v22
	s_and_saveexec_b64 s[12:13], s[6:7]
	v_mov_b32_e32 v5, v23
	v_fmamk_f32 v5, v5, 0x3a800000, v112
	v_mul_f32_e32 v6, 0x4f800000, v5
	v_cmp_gt_f32_e32 vcc, s67, v5
	v_mul_f32_e32 v4, 0x3a800000, v4
	s_nop 0
	v_cndmask_b32_e32 v5, v5, v6, vcc
	v_sqrt_f32_e32 v6, v5
	s_nop 0
	v_add_u32_e32 v7, -1, v6
	v_fma_f32 v9, -v7, v6, v5
	v_add_u32_e32 v8, 1, v6
	v_cmp_ge_f32_e64 s[8:9], 0, v9
	s_nop 1
	v_cndmask_b32_e64 v7, v6, v7, s[8:9]
	v_fma_f32 v6, -v8, v6, v5
	v_cmp_lt_f32_e64 s[8:9], 0, v6
	s_nop 1
	v_cndmask_b32_e64 v6, v7, v8, s[8:9]
	v_mul_f32_e32 v7, 0x37800000, v6
	v_cndmask_b32_e32 v6, v6, v7, vcc
	v_cmp_class_f32_e32 vcc, v5, v113
	s_nop 1
	v_cndmask_b32_e32 v5, v6, v5, vcc
	v_div_scale_f32 v6, s[8:9], v5, v5, 1.0
	v_rcp_f32_e32 v7, v6
	s_nop 0
	v_fma_f32 v8, -v6, v7, 1.0
	v_fmac_f32_e32 v7, v8, v7
	v_div_scale_f32 v8, vcc, 1.0, v5, 1.0
	v_mul_f32_e32 v9, v8, v7
	v_fma_f32 v10, -v6, v9, v8
	v_fmac_f32_e32 v9, v10, v7
	v_fma_f32 v6, -v6, v9, v8
	s_nop 1
	v_div_fmas_f32 v6, v6, v7, v9
	v_div_fixup_f32 v5, v6, v5, 1.0
	ds_write_b64 v62, v[4:5] offset:56
	s_or_b64 exec, exec, s[12:13]
	s_waitcnt vmcnt(14)
	v_mov_b32_e32 v4, v98
	v_mov_b32_e32 v5, v99
	v_mov_b32_e32 v6, v100
	v_mov_b32_e32 v7, v101
	v_mov_b32_e32 v8, v102
	v_mov_b32_e32 v9, v103
	v_mov_b32_e32 v10, v104
	v_mov_b32_e32 v11, v105
	v_lshlrev_b32_e32 v13, 16, v4
	v_and_b32_e32 v14, 0xffff0000, v4
	v_lshlrev_b32_e32 v15, 16, v5
	v_and_b32_e32 v5, 0xffff0000, v5
	v_lshlrev_b32_e32 v16, 16, v6
	v_and_b32_e32 v6, 0xffff0000, v6
	v_lshlrev_b32_e32 v17, 16, v7
	v_and_b32_e32 v7, 0xffff0000, v7
	v_lshlrev_b32_e32 v18, 16, v8
	v_and_b32_e32 v8, 0xffff0000, v8
	v_lshlrev_b32_e32 v19, 16, v9
	v_and_b32_e32 v9, 0xffff0000, v9
	v_lshlrev_b32_e32 v20, 16, v10
	v_and_b32_e32 v10, 0xffff0000, v10
	v_lshlrev_b32_e32 v21, 16, v11
	v_and_b32_e32 v11, 0xffff0000, v11
	v_add_f32_e32 v22, v13, v14
	v_add_f32_e32 v23, v15, v5
	v_add_f32_e32 v24, v16, v6
	v_add_f32_e32 v25, v17, v7
	v_add_f32_e32 v26, v18, v8
	v_add_f32_e32 v27, v19, v9
	v_add_f32_e32 v12, v20, v10
	v_add_f32_e32 v4, v21, v11
	v_add_f32_e32 v22, v22, v23
	v_add_f32_e32 v24, v24, v25
	v_add_f32_e32 v26, v26, v27
	v_add_f32_e32 v4, v12, v4
	v_add_f32_e32 v22, v22, v24
	v_add_f32_e32 v4, v26, v4
	v_add_f32_e32 v4, v22, v4
	s_nop 1
	v_add_f32_dpp v4, v4, v4 row_ror:8 row_mask:0xf bank_mask:0xf bound_ctrl:1
	s_nop 1
	v_add_f32_dpp v4, v4, v4 row_ror:4 row_mask:0xf bank_mask:0xf bound_ctrl:1
	s_nop 1
	v_add_f32_dpp v4, v4, v4 row_ror:2 row_mask:0xf bank_mask:0xf bound_ctrl:1
	s_nop 1
	v_add_f32_dpp v4, v4, v4 row_ror:1 row_mask:0xf bank_mask:0xf bound_ctrl:1
	v_mov_b32_e32 v22, v4
	s_nop 1
	v_permlane16_swap_b32_e32 v4, v22
	v_add_f32_e32 v4, v4, v22
	v_mov_b32_e32 v22, v4
	s_nop 1
	v_permlane32_swap_b32_e32 v4, v22
	v_add_f32_e32 v4, v4, v22
	v_fmac_f32_e32 v13, 0xba800000, v4
	v_fmac_f32_e32 v14, 0xba800000, v4
	v_fmac_f32_e32 v15, 0xba800000, v4
	v_fmac_f32_e32 v5, 0xba800000, v4
	v_fmac_f32_e32 v16, 0xba800000, v4
	v_fmac_f32_e32 v6, 0xba800000, v4
	v_fmac_f32_e32 v17, 0xba800000, v4
	v_fmac_f32_e32 v7, 0xba800000, v4
	v_fmac_f32_e32 v18, 0xba800000, v4
	v_fmac_f32_e32 v8, 0xba800000, v4
	v_fmac_f32_e32 v19, 0xba800000, v4
	v_fmac_f32_e32 v9, 0xba800000, v4
	v_fmac_f32_e32 v20, 0xba800000, v4
	v_fmac_f32_e32 v10, 0xba800000, v4
	v_fmac_f32_e32 v21, 0xba800000, v4
	v_fmac_f32_e32 v11, 0xba800000, v4
	v_mul_f32_e32 v23, v13, v13
	v_fmac_f32_e32 v23, v14, v14
	v_fmac_f32_e32 v23, v15, v15
	v_fmac_f32_e32 v23, v5, v5
	v_fmac_f32_e32 v23, v16, v16
	v_fmac_f32_e32 v23, v6, v6
	v_fmac_f32_e32 v23, v17, v17
	v_fmac_f32_e32 v23, v7, v7
	v_fmac_f32_e32 v23, v18, v18
	v_fmac_f32_e32 v23, v8, v8
	v_fmac_f32_e32 v23, v19, v19
	v_fmac_f32_e32 v23, v9, v9
	v_fmac_f32_e32 v23, v20, v20
	v_fmac_f32_e32 v23, v10, v10
	v_fmac_f32_e32 v23, v21, v21
	v_fmac_f32_e32 v23, v11, v11
	s_nop 1
	v_add_f32_dpp v23, v23, v23 row_ror:8 row_mask:0xf bank_mask:0xf bound_ctrl:1
	s_nop 1
	v_add_f32_dpp v23, v23, v23 row_ror:4 row_mask:0xf bank_mask:0xf bound_ctrl:1
	s_nop 1
	v_add_f32_dpp v23, v23, v23 row_ror:2 row_mask:0xf bank_mask:0xf bound_ctrl:1
	s_nop 1
	v_add_f32_dpp v23, v23, v23 row_ror:1 row_mask:0xf bank_mask:0xf bound_ctrl:1
	v_mov_b32_e32 v22, v23
	s_nop 1
	v_permlane16_swap_b32_e32 v23, v22
	v_add_f32_e32 v23, v23, v22
	v_mov_b32_e32 v22, v23
	s_nop 1
	v_permlane32_swap_b32_e32 v23, v22
	v_add_f32_e32 v23, v23, v22
	s_and_saveexec_b64 s[12:13], s[6:7]
	v_mov_b32_e32 v5, v23
	v_fmamk_f32 v5, v5, 0x3a800000, v112
	v_mul_f32_e32 v6, 0x4f800000, v5
	v_cmp_gt_f32_e32 vcc, s67, v5
	v_mul_f32_e32 v4, 0x3a800000, v4
	s_nop 0
	v_cndmask_b32_e32 v5, v5, v6, vcc
	v_sqrt_f32_e32 v6, v5
	s_nop 0
	v_add_u32_e32 v7, -1, v6
	v_fma_f32 v9, -v7, v6, v5
	v_add_u32_e32 v8, 1, v6
	v_cmp_ge_f32_e64 s[8:9], 0, v9
	s_nop 1
	v_cndmask_b32_e64 v7, v6, v7, s[8:9]
	v_fma_f32 v6, -v8, v6, v5
	v_cmp_lt_f32_e64 s[8:9], 0, v6
	s_nop 1
	v_cndmask_b32_e64 v6, v7, v8, s[8:9]
	v_mul_f32_e32 v7, 0x37800000, v6
	v_cndmask_b32_e32 v6, v6, v7, vcc
	v_cmp_class_f32_e32 vcc, v5, v113
	s_nop 1
	v_cndmask_b32_e32 v5, v6, v5, vcc
	v_div_scale_f32 v6, s[8:9], v5, v5, 1.0
	v_rcp_f32_e32 v7, v6
	s_nop 0
	v_fma_f32 v8, -v6, v7, 1.0
	v_fmac_f32_e32 v7, v8, v7
	v_div_scale_f32 v8, vcc, 1.0, v5, 1.0
	v_mul_f32_e32 v9, v8, v7
	v_fma_f32 v10, -v6, v9, v8
	v_fmac_f32_e32 v9, v10, v7
	v_fma_f32 v6, -v6, v9, v8
	s_nop 1
	v_div_fmas_f32 v6, v6, v7, v9
	v_div_fixup_f32 v5, v6, v5, 1.0
	ds_write_b64 v62, v[4:5] offset:64
	s_or_b64 exec, exec, s[12:13]
	s_waitcnt vmcnt(12)
	v_mov_b32_e32 v4, v122
	v_mov_b32_e32 v5, v123
	v_mov_b32_e32 v6, v124
	v_mov_b32_e32 v7, v125
	v_mov_b32_e32 v8, v126
	v_mov_b32_e32 v9, v127
	v_mov_b32_e32 v10, v128
	v_mov_b32_e32 v11, v129
	v_lshlrev_b32_e32 v13, 16, v4
	v_and_b32_e32 v14, 0xffff0000, v4
	v_lshlrev_b32_e32 v15, 16, v5
	v_and_b32_e32 v5, 0xffff0000, v5
	v_lshlrev_b32_e32 v16, 16, v6
	v_and_b32_e32 v6, 0xffff0000, v6
	v_lshlrev_b32_e32 v17, 16, v7
	v_and_b32_e32 v7, 0xffff0000, v7
	v_lshlrev_b32_e32 v18, 16, v8
	v_and_b32_e32 v8, 0xffff0000, v8
	v_lshlrev_b32_e32 v19, 16, v9
	v_and_b32_e32 v9, 0xffff0000, v9
	v_lshlrev_b32_e32 v20, 16, v10
	v_and_b32_e32 v10, 0xffff0000, v10
	v_lshlrev_b32_e32 v21, 16, v11
	v_and_b32_e32 v11, 0xffff0000, v11
	v_add_f32_e32 v22, v13, v14
	v_add_f32_e32 v23, v15, v5
	v_add_f32_e32 v24, v16, v6
	v_add_f32_e32 v25, v17, v7
	v_add_f32_e32 v26, v18, v8
	v_add_f32_e32 v27, v19, v9
	v_add_f32_e32 v12, v20, v10
	v_add_f32_e32 v4, v21, v11
	v_add_f32_e32 v22, v22, v23
	v_add_f32_e32 v24, v24, v25
	v_add_f32_e32 v26, v26, v27
	v_add_f32_e32 v4, v12, v4
	v_add_f32_e32 v22, v22, v24
	v_add_f32_e32 v4, v26, v4
	v_add_f32_e32 v4, v22, v4
	s_nop 1
	v_add_f32_dpp v4, v4, v4 row_ror:8 row_mask:0xf bank_mask:0xf bound_ctrl:1
	s_nop 1
	v_add_f32_dpp v4, v4, v4 row_ror:4 row_mask:0xf bank_mask:0xf bound_ctrl:1
	s_nop 1
	v_add_f32_dpp v4, v4, v4 row_ror:2 row_mask:0xf bank_mask:0xf bound_ctrl:1
	s_nop 1
	v_add_f32_dpp v4, v4, v4 row_ror:1 row_mask:0xf bank_mask:0xf bound_ctrl:1
	v_mov_b32_e32 v22, v4
	s_nop 1
	v_permlane16_swap_b32_e32 v4, v22
	v_add_f32_e32 v4, v4, v22
	v_mov_b32_e32 v22, v4
	s_nop 1
	v_permlane32_swap_b32_e32 v4, v22
	v_add_f32_e32 v4, v4, v22
	v_fmac_f32_e32 v13, 0xba800000, v4
	v_fmac_f32_e32 v14, 0xba800000, v4
	v_fmac_f32_e32 v15, 0xba800000, v4
	v_fmac_f32_e32 v5, 0xba800000, v4
	v_fmac_f32_e32 v16, 0xba800000, v4
	v_fmac_f32_e32 v6, 0xba800000, v4
	v_fmac_f32_e32 v17, 0xba800000, v4
	v_fmac_f32_e32 v7, 0xba800000, v4
	v_fmac_f32_e32 v18, 0xba800000, v4
	v_fmac_f32_e32 v8, 0xba800000, v4
	v_fmac_f32_e32 v19, 0xba800000, v4
	v_fmac_f32_e32 v9, 0xba800000, v4
	v_fmac_f32_e32 v20, 0xba800000, v4
	v_fmac_f32_e32 v10, 0xba800000, v4
	v_fmac_f32_e32 v21, 0xba800000, v4
	v_fmac_f32_e32 v11, 0xba800000, v4
	v_mul_f32_e32 v23, v13, v13
	v_fmac_f32_e32 v23, v14, v14
	v_fmac_f32_e32 v23, v15, v15
	v_fmac_f32_e32 v23, v5, v5
	v_fmac_f32_e32 v23, v16, v16
	v_fmac_f32_e32 v23, v6, v6
	v_fmac_f32_e32 v23, v17, v17
	v_fmac_f32_e32 v23, v7, v7
	v_fmac_f32_e32 v23, v18, v18
	v_fmac_f32_e32 v23, v8, v8
	v_fmac_f32_e32 v23, v19, v19
	v_fmac_f32_e32 v23, v9, v9
	v_fmac_f32_e32 v23, v20, v20
	v_fmac_f32_e32 v23, v10, v10
	v_fmac_f32_e32 v23, v21, v21
	v_fmac_f32_e32 v23, v11, v11
	s_nop 1
	v_add_f32_dpp v23, v23, v23 row_ror:8 row_mask:0xf bank_mask:0xf bound_ctrl:1
	s_nop 1
	v_add_f32_dpp v23, v23, v23 row_ror:4 row_mask:0xf bank_mask:0xf bound_ctrl:1
	s_nop 1
	v_add_f32_dpp v23, v23, v23 row_ror:2 row_mask:0xf bank_mask:0xf bound_ctrl:1
	s_nop 1
	v_add_f32_dpp v23, v23, v23 row_ror:1 row_mask:0xf bank_mask:0xf bound_ctrl:1
	v_mov_b32_e32 v22, v23
	s_nop 1
	v_permlane16_swap_b32_e32 v23, v22
	v_add_f32_e32 v23, v23, v22
	v_mov_b32_e32 v22, v23
	s_nop 1
	v_permlane32_swap_b32_e32 v23, v22
	v_add_f32_e32 v23, v23, v22
	s_and_saveexec_b64 s[12:13], s[6:7]
	v_mov_b32_e32 v5, v23
	v_fmamk_f32 v5, v5, 0x3a800000, v112
	v_mul_f32_e32 v6, 0x4f800000, v5
	v_cmp_gt_f32_e32 vcc, s67, v5
	v_mul_f32_e32 v4, 0x3a800000, v4
	s_nop 0
	v_cndmask_b32_e32 v5, v5, v6, vcc
	v_sqrt_f32_e32 v6, v5
	s_nop 0
	v_add_u32_e32 v7, -1, v6
	v_fma_f32 v9, -v7, v6, v5
	v_add_u32_e32 v8, 1, v6
	v_cmp_ge_f32_e64 s[8:9], 0, v9
	s_nop 1
	v_cndmask_b32_e64 v7, v6, v7, s[8:9]
	v_fma_f32 v6, -v8, v6, v5
	v_cmp_lt_f32_e64 s[8:9], 0, v6
	s_nop 1
	v_cndmask_b32_e64 v6, v7, v8, s[8:9]
	v_mul_f32_e32 v7, 0x37800000, v6
	v_cndmask_b32_e32 v6, v6, v7, vcc
	v_cmp_class_f32_e32 vcc, v5, v113
	s_nop 1
	v_cndmask_b32_e32 v5, v6, v5, vcc
	v_div_scale_f32 v6, s[8:9], v5, v5, 1.0
	v_rcp_f32_e32 v7, v6
	s_nop 0
	v_fma_f32 v8, -v6, v7, 1.0
	v_fmac_f32_e32 v7, v8, v7
	v_div_scale_f32 v8, vcc, 1.0, v5, 1.0
	v_mul_f32_e32 v9, v8, v7
	v_fma_f32 v10, -v6, v9, v8
	v_fmac_f32_e32 v9, v10, v7
	v_fma_f32 v6, -v6, v9, v8
	s_nop 1
	v_div_fmas_f32 v6, v6, v7, v9
	v_div_fixup_f32 v5, v6, v5, 1.0
	ds_write_b64 v62, v[4:5] offset:72
	s_or_b64 exec, exec, s[12:13]
	s_waitcnt vmcnt(10)
	v_mov_b32_e32 v4, v130
	v_mov_b32_e32 v5, v131
	v_mov_b32_e32 v6, v132
	v_mov_b32_e32 v7, v133
	v_mov_b32_e32 v8, v134
	v_mov_b32_e32 v9, v135
	v_mov_b32_e32 v10, v136
	v_mov_b32_e32 v11, v137
	v_lshlrev_b32_e32 v13, 16, v4
	v_and_b32_e32 v14, 0xffff0000, v4
	v_lshlrev_b32_e32 v15, 16, v5
	v_and_b32_e32 v5, 0xffff0000, v5
	v_lshlrev_b32_e32 v16, 16, v6
	v_and_b32_e32 v6, 0xffff0000, v6
	v_lshlrev_b32_e32 v17, 16, v7
	v_and_b32_e32 v7, 0xffff0000, v7
	v_lshlrev_b32_e32 v18, 16, v8
	v_and_b32_e32 v8, 0xffff0000, v8
	v_lshlrev_b32_e32 v19, 16, v9
	v_and_b32_e32 v9, 0xffff0000, v9
	v_lshlrev_b32_e32 v20, 16, v10
	v_and_b32_e32 v10, 0xffff0000, v10
	v_lshlrev_b32_e32 v21, 16, v11
	v_and_b32_e32 v11, 0xffff0000, v11
	v_add_f32_e32 v22, v13, v14
	v_add_f32_e32 v23, v15, v5
	v_add_f32_e32 v24, v16, v6
	v_add_f32_e32 v25, v17, v7
	v_add_f32_e32 v26, v18, v8
	v_add_f32_e32 v27, v19, v9
	v_add_f32_e32 v12, v20, v10
	v_add_f32_e32 v4, v21, v11
	v_add_f32_e32 v22, v22, v23
	v_add_f32_e32 v24, v24, v25
	v_add_f32_e32 v26, v26, v27
	v_add_f32_e32 v4, v12, v4
	v_add_f32_e32 v22, v22, v24
	v_add_f32_e32 v4, v26, v4
	v_add_f32_e32 v4, v22, v4
	s_nop 1
	v_add_f32_dpp v4, v4, v4 row_ror:8 row_mask:0xf bank_mask:0xf bound_ctrl:1
	s_nop 1
	v_add_f32_dpp v4, v4, v4 row_ror:4 row_mask:0xf bank_mask:0xf bound_ctrl:1
	s_nop 1
	v_add_f32_dpp v4, v4, v4 row_ror:2 row_mask:0xf bank_mask:0xf bound_ctrl:1
	s_nop 1
	v_add_f32_dpp v4, v4, v4 row_ror:1 row_mask:0xf bank_mask:0xf bound_ctrl:1
	v_mov_b32_e32 v22, v4
	s_nop 1
	v_permlane16_swap_b32_e32 v4, v22
	v_add_f32_e32 v4, v4, v22
	v_mov_b32_e32 v22, v4
	s_nop 1
	v_permlane32_swap_b32_e32 v4, v22
	v_add_f32_e32 v4, v4, v22
	v_fmac_f32_e32 v13, 0xba800000, v4
	v_fmac_f32_e32 v14, 0xba800000, v4
	v_fmac_f32_e32 v15, 0xba800000, v4
	v_fmac_f32_e32 v5, 0xba800000, v4
	v_fmac_f32_e32 v16, 0xba800000, v4
	v_fmac_f32_e32 v6, 0xba800000, v4
	v_fmac_f32_e32 v17, 0xba800000, v4
	v_fmac_f32_e32 v7, 0xba800000, v4
	v_fmac_f32_e32 v18, 0xba800000, v4
	v_fmac_f32_e32 v8, 0xba800000, v4
	v_fmac_f32_e32 v19, 0xba800000, v4
	v_fmac_f32_e32 v9, 0xba800000, v4
	v_fmac_f32_e32 v20, 0xba800000, v4
	v_fmac_f32_e32 v10, 0xba800000, v4
	v_fmac_f32_e32 v21, 0xba800000, v4
	v_fmac_f32_e32 v11, 0xba800000, v4
	v_mul_f32_e32 v23, v13, v13
	v_fmac_f32_e32 v23, v14, v14
	v_fmac_f32_e32 v23, v15, v15
	v_fmac_f32_e32 v23, v5, v5
	v_fmac_f32_e32 v23, v16, v16
	v_fmac_f32_e32 v23, v6, v6
	v_fmac_f32_e32 v23, v17, v17
	v_fmac_f32_e32 v23, v7, v7
	v_fmac_f32_e32 v23, v18, v18
	v_fmac_f32_e32 v23, v8, v8
	v_fmac_f32_e32 v23, v19, v19
	v_fmac_f32_e32 v23, v9, v9
	v_fmac_f32_e32 v23, v20, v20
	v_fmac_f32_e32 v23, v10, v10
	v_fmac_f32_e32 v23, v21, v21
	v_fmac_f32_e32 v23, v11, v11
	s_nop 1
	v_add_f32_dpp v23, v23, v23 row_ror:8 row_mask:0xf bank_mask:0xf bound_ctrl:1
	s_nop 1
	v_add_f32_dpp v23, v23, v23 row_ror:4 row_mask:0xf bank_mask:0xf bound_ctrl:1
	s_nop 1
	v_add_f32_dpp v23, v23, v23 row_ror:2 row_mask:0xf bank_mask:0xf bound_ctrl:1
	s_nop 1
	v_add_f32_dpp v23, v23, v23 row_ror:1 row_mask:0xf bank_mask:0xf bound_ctrl:1
	v_mov_b32_e32 v22, v23
	s_nop 1
	v_permlane16_swap_b32_e32 v23, v22
	v_add_f32_e32 v23, v23, v22
	v_mov_b32_e32 v22, v23
	s_nop 1
	v_permlane32_swap_b32_e32 v23, v22
	v_add_f32_e32 v23, v23, v22
	s_and_saveexec_b64 s[12:13], s[6:7]
	v_mov_b32_e32 v5, v23
	v_fmamk_f32 v5, v5, 0x3a800000, v112
	v_mul_f32_e32 v6, 0x4f800000, v5
	v_cmp_gt_f32_e32 vcc, s67, v5
	v_mul_f32_e32 v4, 0x3a800000, v4
	s_nop 0
	v_cndmask_b32_e32 v5, v5, v6, vcc
	v_sqrt_f32_e32 v6, v5
	s_nop 0
	v_add_u32_e32 v7, -1, v6
	v_fma_f32 v9, -v7, v6, v5
	v_add_u32_e32 v8, 1, v6
	v_cmp_ge_f32_e64 s[8:9], 0, v9
	s_nop 1
	v_cndmask_b32_e64 v7, v6, v7, s[8:9]
	v_fma_f32 v6, -v8, v6, v5
	v_cmp_lt_f32_e64 s[8:9], 0, v6
	s_nop 1
	v_cndmask_b32_e64 v6, v7, v8, s[8:9]
	v_mul_f32_e32 v7, 0x37800000, v6
	v_cndmask_b32_e32 v6, v6, v7, vcc
	v_cmp_class_f32_e32 vcc, v5, v113
	s_nop 1
	v_cndmask_b32_e32 v5, v6, v5, vcc
	v_div_scale_f32 v6, s[8:9], v5, v5, 1.0
	v_rcp_f32_e32 v7, v6
	s_nop 0
	v_fma_f32 v8, -v6, v7, 1.0
	v_fmac_f32_e32 v7, v8, v7
	v_div_scale_f32 v8, vcc, 1.0, v5, 1.0
	v_mul_f32_e32 v9, v8, v7
	v_fma_f32 v10, -v6, v9, v8
	v_fmac_f32_e32 v9, v10, v7
	v_fma_f32 v6, -v6, v9, v8
	s_nop 1
	v_div_fmas_f32 v6, v6, v7, v9
	v_div_fixup_f32 v5, v6, v5, 1.0
	ds_write_b64 v62, v[4:5] offset:80
	s_or_b64 exec, exec, s[12:13]
	s_waitcnt vmcnt(8)
	v_mov_b32_e32 v4, v138
	v_mov_b32_e32 v5, v139
	v_mov_b32_e32 v6, v140
	v_mov_b32_e32 v7, v141
	v_mov_b32_e32 v8, v142
	v_mov_b32_e32 v9, v143
	v_mov_b32_e32 v10, v144
	v_mov_b32_e32 v11, v145
	v_lshlrev_b32_e32 v13, 16, v4
	v_and_b32_e32 v14, 0xffff0000, v4
	v_lshlrev_b32_e32 v15, 16, v5
	v_and_b32_e32 v5, 0xffff0000, v5
	v_lshlrev_b32_e32 v16, 16, v6
	v_and_b32_e32 v6, 0xffff0000, v6
	v_lshlrev_b32_e32 v17, 16, v7
	v_and_b32_e32 v7, 0xffff0000, v7
	v_lshlrev_b32_e32 v18, 16, v8
	v_and_b32_e32 v8, 0xffff0000, v8
	v_lshlrev_b32_e32 v19, 16, v9
	v_and_b32_e32 v9, 0xffff0000, v9
	v_lshlrev_b32_e32 v20, 16, v10
	v_and_b32_e32 v10, 0xffff0000, v10
	v_lshlrev_b32_e32 v21, 16, v11
	v_and_b32_e32 v11, 0xffff0000, v11
	v_add_f32_e32 v22, v13, v14
	v_add_f32_e32 v23, v15, v5
	v_add_f32_e32 v24, v16, v6
	v_add_f32_e32 v25, v17, v7
	v_add_f32_e32 v26, v18, v8
	v_add_f32_e32 v27, v19, v9
	v_add_f32_e32 v12, v20, v10
	v_add_f32_e32 v4, v21, v11
	v_add_f32_e32 v22, v22, v23
	v_add_f32_e32 v24, v24, v25
	v_add_f32_e32 v26, v26, v27
	v_add_f32_e32 v4, v12, v4
	v_add_f32_e32 v22, v22, v24
	v_add_f32_e32 v4, v26, v4
	v_add_f32_e32 v4, v22, v4
	s_nop 1
	v_add_f32_dpp v4, v4, v4 row_ror:8 row_mask:0xf bank_mask:0xf bound_ctrl:1
	s_nop 1
	v_add_f32_dpp v4, v4, v4 row_ror:4 row_mask:0xf bank_mask:0xf bound_ctrl:1
	s_nop 1
	v_add_f32_dpp v4, v4, v4 row_ror:2 row_mask:0xf bank_mask:0xf bound_ctrl:1
	s_nop 1
	v_add_f32_dpp v4, v4, v4 row_ror:1 row_mask:0xf bank_mask:0xf bound_ctrl:1
	v_mov_b32_e32 v22, v4
	s_nop 1
	v_permlane16_swap_b32_e32 v4, v22
	v_add_f32_e32 v4, v4, v22
	v_mov_b32_e32 v22, v4
	s_nop 1
	v_permlane32_swap_b32_e32 v4, v22
	v_add_f32_e32 v4, v4, v22
	v_fmac_f32_e32 v13, 0xba800000, v4
	v_fmac_f32_e32 v14, 0xba800000, v4
	v_fmac_f32_e32 v15, 0xba800000, v4
	v_fmac_f32_e32 v5, 0xba800000, v4
	v_fmac_f32_e32 v16, 0xba800000, v4
	v_fmac_f32_e32 v6, 0xba800000, v4
	v_fmac_f32_e32 v17, 0xba800000, v4
	v_fmac_f32_e32 v7, 0xba800000, v4
	v_fmac_f32_e32 v18, 0xba800000, v4
	v_fmac_f32_e32 v8, 0xba800000, v4
	v_fmac_f32_e32 v19, 0xba800000, v4
	v_fmac_f32_e32 v9, 0xba800000, v4
	v_fmac_f32_e32 v20, 0xba800000, v4
	v_fmac_f32_e32 v10, 0xba800000, v4
	v_fmac_f32_e32 v21, 0xba800000, v4
	v_fmac_f32_e32 v11, 0xba800000, v4
	v_mul_f32_e32 v23, v13, v13
	v_fmac_f32_e32 v23, v14, v14
	v_fmac_f32_e32 v23, v15, v15
	v_fmac_f32_e32 v23, v5, v5
	v_fmac_f32_e32 v23, v16, v16
	v_fmac_f32_e32 v23, v6, v6
	v_fmac_f32_e32 v23, v17, v17
	v_fmac_f32_e32 v23, v7, v7
	v_fmac_f32_e32 v23, v18, v18
	v_fmac_f32_e32 v23, v8, v8
	v_fmac_f32_e32 v23, v19, v19
	v_fmac_f32_e32 v23, v9, v9
	v_fmac_f32_e32 v23, v20, v20
	v_fmac_f32_e32 v23, v10, v10
	v_fmac_f32_e32 v23, v21, v21
	v_fmac_f32_e32 v23, v11, v11
	s_nop 1
	v_add_f32_dpp v23, v23, v23 row_ror:8 row_mask:0xf bank_mask:0xf bound_ctrl:1
	s_nop 1
	v_add_f32_dpp v23, v23, v23 row_ror:4 row_mask:0xf bank_mask:0xf bound_ctrl:1
	s_nop 1
	v_add_f32_dpp v23, v23, v23 row_ror:2 row_mask:0xf bank_mask:0xf bound_ctrl:1
	s_nop 1
	v_add_f32_dpp v23, v23, v23 row_ror:1 row_mask:0xf bank_mask:0xf bound_ctrl:1
	v_mov_b32_e32 v22, v23
	s_nop 1
	v_permlane16_swap_b32_e32 v23, v22
	v_add_f32_e32 v23, v23, v22
	v_mov_b32_e32 v22, v23
	s_nop 1
	v_permlane32_swap_b32_e32 v23, v22
	v_add_f32_e32 v23, v23, v22
	s_and_saveexec_b64 s[12:13], s[6:7]
	v_mov_b32_e32 v5, v23
	v_fmamk_f32 v5, v5, 0x3a800000, v112
	v_mul_f32_e32 v6, 0x4f800000, v5
	v_cmp_gt_f32_e32 vcc, s67, v5
	v_mul_f32_e32 v4, 0x3a800000, v4
	s_nop 0
	v_cndmask_b32_e32 v5, v5, v6, vcc
	v_sqrt_f32_e32 v6, v5
	s_nop 0
	v_add_u32_e32 v7, -1, v6
	v_fma_f32 v9, -v7, v6, v5
	v_add_u32_e32 v8, 1, v6
	v_cmp_ge_f32_e64 s[8:9], 0, v9
	s_nop 1
	v_cndmask_b32_e64 v7, v6, v7, s[8:9]
	v_fma_f32 v6, -v8, v6, v5
	v_cmp_lt_f32_e64 s[8:9], 0, v6
	s_nop 1
	v_cndmask_b32_e64 v6, v7, v8, s[8:9]
	v_mul_f32_e32 v7, 0x37800000, v6
	v_cndmask_b32_e32 v6, v6, v7, vcc
	v_cmp_class_f32_e32 vcc, v5, v113
	s_nop 1
	v_cndmask_b32_e32 v5, v6, v5, vcc
	v_div_scale_f32 v6, s[8:9], v5, v5, 1.0
	v_rcp_f32_e32 v7, v6
	s_nop 0
	v_fma_f32 v8, -v6, v7, 1.0
	v_fmac_f32_e32 v7, v8, v7
	v_div_scale_f32 v8, vcc, 1.0, v5, 1.0
	v_mul_f32_e32 v9, v8, v7
	v_fma_f32 v10, -v6, v9, v8
	v_fmac_f32_e32 v9, v10, v7
	v_fma_f32 v6, -v6, v9, v8
	s_nop 1
	v_div_fmas_f32 v6, v6, v7, v9
	v_div_fixup_f32 v5, v6, v5, 1.0
	ds_write_b64 v62, v[4:5] offset:88
	s_or_b64 exec, exec, s[12:13]
	s_waitcnt vmcnt(6)
	v_mov_b32_e32 v4, v146
	v_mov_b32_e32 v5, v147
	v_mov_b32_e32 v6, v148
	v_mov_b32_e32 v7, v149
	v_mov_b32_e32 v8, v150
	v_mov_b32_e32 v9, v151
	v_mov_b32_e32 v10, v152
	v_mov_b32_e32 v11, v153
	v_lshlrev_b32_e32 v13, 16, v4
	v_and_b32_e32 v14, 0xffff0000, v4
	v_lshlrev_b32_e32 v15, 16, v5
	v_and_b32_e32 v5, 0xffff0000, v5
	v_lshlrev_b32_e32 v16, 16, v6
	v_and_b32_e32 v6, 0xffff0000, v6
	v_lshlrev_b32_e32 v17, 16, v7
	v_and_b32_e32 v7, 0xffff0000, v7
	v_lshlrev_b32_e32 v18, 16, v8
	v_and_b32_e32 v8, 0xffff0000, v8
	v_lshlrev_b32_e32 v19, 16, v9
	v_and_b32_e32 v9, 0xffff0000, v9
	v_lshlrev_b32_e32 v20, 16, v10
	v_and_b32_e32 v10, 0xffff0000, v10
	v_lshlrev_b32_e32 v21, 16, v11
	v_and_b32_e32 v11, 0xffff0000, v11
	v_add_f32_e32 v22, v13, v14
	v_add_f32_e32 v23, v15, v5
	v_add_f32_e32 v24, v16, v6
	v_add_f32_e32 v25, v17, v7
	v_add_f32_e32 v26, v18, v8
	v_add_f32_e32 v27, v19, v9
	v_add_f32_e32 v12, v20, v10
	v_add_f32_e32 v4, v21, v11
	v_add_f32_e32 v22, v22, v23
	v_add_f32_e32 v24, v24, v25
	v_add_f32_e32 v26, v26, v27
	v_add_f32_e32 v4, v12, v4
	v_add_f32_e32 v22, v22, v24
	v_add_f32_e32 v4, v26, v4
	v_add_f32_e32 v4, v22, v4
	s_nop 1
	v_add_f32_dpp v4, v4, v4 row_ror:8 row_mask:0xf bank_mask:0xf bound_ctrl:1
	s_nop 1
	v_add_f32_dpp v4, v4, v4 row_ror:4 row_mask:0xf bank_mask:0xf bound_ctrl:1
	s_nop 1
	v_add_f32_dpp v4, v4, v4 row_ror:2 row_mask:0xf bank_mask:0xf bound_ctrl:1
	s_nop 1
	v_add_f32_dpp v4, v4, v4 row_ror:1 row_mask:0xf bank_mask:0xf bound_ctrl:1
	v_mov_b32_e32 v22, v4
	s_nop 1
	v_permlane16_swap_b32_e32 v4, v22
	v_add_f32_e32 v4, v4, v22
	v_mov_b32_e32 v22, v4
	s_nop 1
	v_permlane32_swap_b32_e32 v4, v22
	v_add_f32_e32 v4, v4, v22
	v_fmac_f32_e32 v13, 0xba800000, v4
	v_fmac_f32_e32 v14, 0xba800000, v4
	v_fmac_f32_e32 v15, 0xba800000, v4
	v_fmac_f32_e32 v5, 0xba800000, v4
	v_fmac_f32_e32 v16, 0xba800000, v4
	v_fmac_f32_e32 v6, 0xba800000, v4
	v_fmac_f32_e32 v17, 0xba800000, v4
	v_fmac_f32_e32 v7, 0xba800000, v4
	v_fmac_f32_e32 v18, 0xba800000, v4
	v_fmac_f32_e32 v8, 0xba800000, v4
	v_fmac_f32_e32 v19, 0xba800000, v4
	v_fmac_f32_e32 v9, 0xba800000, v4
	v_fmac_f32_e32 v20, 0xba800000, v4
	v_fmac_f32_e32 v10, 0xba800000, v4
	v_fmac_f32_e32 v21, 0xba800000, v4
	v_fmac_f32_e32 v11, 0xba800000, v4
	v_mul_f32_e32 v23, v13, v13
	v_fmac_f32_e32 v23, v14, v14
	v_fmac_f32_e32 v23, v15, v15
	v_fmac_f32_e32 v23, v5, v5
	v_fmac_f32_e32 v23, v16, v16
	v_fmac_f32_e32 v23, v6, v6
	v_fmac_f32_e32 v23, v17, v17
	v_fmac_f32_e32 v23, v7, v7
	v_fmac_f32_e32 v23, v18, v18
	v_fmac_f32_e32 v23, v8, v8
	v_fmac_f32_e32 v23, v19, v19
	v_fmac_f32_e32 v23, v9, v9
	v_fmac_f32_e32 v23, v20, v20
	v_fmac_f32_e32 v23, v10, v10
	v_fmac_f32_e32 v23, v21, v21
	v_fmac_f32_e32 v23, v11, v11
	s_nop 1
	v_add_f32_dpp v23, v23, v23 row_ror:8 row_mask:0xf bank_mask:0xf bound_ctrl:1
	s_nop 1
	v_add_f32_dpp v23, v23, v23 row_ror:4 row_mask:0xf bank_mask:0xf bound_ctrl:1
	s_nop 1
	v_add_f32_dpp v23, v23, v23 row_ror:2 row_mask:0xf bank_mask:0xf bound_ctrl:1
	s_nop 1
	v_add_f32_dpp v23, v23, v23 row_ror:1 row_mask:0xf bank_mask:0xf bound_ctrl:1
	v_mov_b32_e32 v22, v23
	s_nop 1
	v_permlane16_swap_b32_e32 v23, v22
	v_add_f32_e32 v23, v23, v22
	v_mov_b32_e32 v22, v23
	s_nop 1
	v_permlane32_swap_b32_e32 v23, v22
	v_add_f32_e32 v23, v23, v22
	s_and_saveexec_b64 s[12:13], s[6:7]
	v_mov_b32_e32 v5, v23
	v_fmamk_f32 v5, v5, 0x3a800000, v112
	v_mul_f32_e32 v6, 0x4f800000, v5
	v_cmp_gt_f32_e32 vcc, s67, v5
	v_mul_f32_e32 v4, 0x3a800000, v4
	s_nop 0
	v_cndmask_b32_e32 v5, v5, v6, vcc
	v_sqrt_f32_e32 v6, v5
	s_nop 0
	v_add_u32_e32 v7, -1, v6
	v_fma_f32 v9, -v7, v6, v5
	v_add_u32_e32 v8, 1, v6
	v_cmp_ge_f32_e64 s[8:9], 0, v9
	s_nop 1
	v_cndmask_b32_e64 v7, v6, v7, s[8:9]
	v_fma_f32 v6, -v8, v6, v5
	v_cmp_lt_f32_e64 s[8:9], 0, v6
	s_nop 1
	v_cndmask_b32_e64 v6, v7, v8, s[8:9]
	v_mul_f32_e32 v7, 0x37800000, v6
	v_cndmask_b32_e32 v6, v6, v7, vcc
	v_cmp_class_f32_e32 vcc, v5, v113
	s_nop 1
	v_cndmask_b32_e32 v5, v6, v5, vcc
	v_div_scale_f32 v6, s[8:9], v5, v5, 1.0
	v_rcp_f32_e32 v7, v6
	s_nop 0
	v_fma_f32 v8, -v6, v7, 1.0
	v_fmac_f32_e32 v7, v8, v7
	v_div_scale_f32 v8, vcc, 1.0, v5, 1.0
	v_mul_f32_e32 v9, v8, v7
	v_fma_f32 v10, -v6, v9, v8
	v_fmac_f32_e32 v9, v10, v7
	v_fma_f32 v6, -v6, v9, v8
	s_nop 1
	v_div_fmas_f32 v6, v6, v7, v9
	v_div_fixup_f32 v5, v6, v5, 1.0
	ds_write_b64 v62, v[4:5] offset:96
	s_or_b64 exec, exec, s[12:13]
	s_waitcnt vmcnt(4)
	v_mov_b32_e32 v4, v154
	v_mov_b32_e32 v5, v155
	v_mov_b32_e32 v6, v156
	v_mov_b32_e32 v7, v157
	v_mov_b32_e32 v8, v158
	v_mov_b32_e32 v9, v159
	v_mov_b32_e32 v10, v160
	v_mov_b32_e32 v11, v161
	v_lshlrev_b32_e32 v13, 16, v4
	v_and_b32_e32 v14, 0xffff0000, v4
	v_lshlrev_b32_e32 v15, 16, v5
	v_and_b32_e32 v5, 0xffff0000, v5
	v_lshlrev_b32_e32 v16, 16, v6
	v_and_b32_e32 v6, 0xffff0000, v6
	v_lshlrev_b32_e32 v17, 16, v7
	v_and_b32_e32 v7, 0xffff0000, v7
	v_lshlrev_b32_e32 v18, 16, v8
	v_and_b32_e32 v8, 0xffff0000, v8
	v_lshlrev_b32_e32 v19, 16, v9
	v_and_b32_e32 v9, 0xffff0000, v9
	v_lshlrev_b32_e32 v20, 16, v10
	v_and_b32_e32 v10, 0xffff0000, v10
	v_lshlrev_b32_e32 v21, 16, v11
	v_and_b32_e32 v11, 0xffff0000, v11
	v_add_f32_e32 v22, v13, v14
	v_add_f32_e32 v23, v15, v5
	v_add_f32_e32 v24, v16, v6
	v_add_f32_e32 v25, v17, v7
	v_add_f32_e32 v26, v18, v8
	v_add_f32_e32 v27, v19, v9
	v_add_f32_e32 v12, v20, v10
	v_add_f32_e32 v4, v21, v11
	v_add_f32_e32 v22, v22, v23
	v_add_f32_e32 v24, v24, v25
	v_add_f32_e32 v26, v26, v27
	v_add_f32_e32 v4, v12, v4
	v_add_f32_e32 v22, v22, v24
	v_add_f32_e32 v4, v26, v4
	v_add_f32_e32 v4, v22, v4
	s_nop 1
	v_add_f32_dpp v4, v4, v4 row_ror:8 row_mask:0xf bank_mask:0xf bound_ctrl:1
	s_nop 1
	v_add_f32_dpp v4, v4, v4 row_ror:4 row_mask:0xf bank_mask:0xf bound_ctrl:1
	s_nop 1
	v_add_f32_dpp v4, v4, v4 row_ror:2 row_mask:0xf bank_mask:0xf bound_ctrl:1
	s_nop 1
	v_add_f32_dpp v4, v4, v4 row_ror:1 row_mask:0xf bank_mask:0xf bound_ctrl:1
	v_mov_b32_e32 v22, v4
	s_nop 1
	v_permlane16_swap_b32_e32 v4, v22
	v_add_f32_e32 v4, v4, v22
	v_mov_b32_e32 v22, v4
	s_nop 1
	v_permlane32_swap_b32_e32 v4, v22
	v_add_f32_e32 v4, v4, v22
	v_fmac_f32_e32 v13, 0xba800000, v4
	v_fmac_f32_e32 v14, 0xba800000, v4
	v_fmac_f32_e32 v15, 0xba800000, v4
	v_fmac_f32_e32 v5, 0xba800000, v4
	v_fmac_f32_e32 v16, 0xba800000, v4
	v_fmac_f32_e32 v6, 0xba800000, v4
	v_fmac_f32_e32 v17, 0xba800000, v4
	v_fmac_f32_e32 v7, 0xba800000, v4
	v_fmac_f32_e32 v18, 0xba800000, v4
	v_fmac_f32_e32 v8, 0xba800000, v4
	v_fmac_f32_e32 v19, 0xba800000, v4
	v_fmac_f32_e32 v9, 0xba800000, v4
	v_fmac_f32_e32 v20, 0xba800000, v4
	v_fmac_f32_e32 v10, 0xba800000, v4
	v_fmac_f32_e32 v21, 0xba800000, v4
	v_fmac_f32_e32 v11, 0xba800000, v4
	v_mul_f32_e32 v23, v13, v13
	v_fmac_f32_e32 v23, v14, v14
	v_fmac_f32_e32 v23, v15, v15
	v_fmac_f32_e32 v23, v5, v5
	v_fmac_f32_e32 v23, v16, v16
	v_fmac_f32_e32 v23, v6, v6
	v_fmac_f32_e32 v23, v17, v17
	v_fmac_f32_e32 v23, v7, v7
	v_fmac_f32_e32 v23, v18, v18
	v_fmac_f32_e32 v23, v8, v8
	v_fmac_f32_e32 v23, v19, v19
	v_fmac_f32_e32 v23, v9, v9
	v_fmac_f32_e32 v23, v20, v20
	v_fmac_f32_e32 v23, v10, v10
	v_fmac_f32_e32 v23, v21, v21
	v_fmac_f32_e32 v23, v11, v11
	s_nop 1
	v_add_f32_dpp v23, v23, v23 row_ror:8 row_mask:0xf bank_mask:0xf bound_ctrl:1
	s_nop 1
	v_add_f32_dpp v23, v23, v23 row_ror:4 row_mask:0xf bank_mask:0xf bound_ctrl:1
	s_nop 1
	v_add_f32_dpp v23, v23, v23 row_ror:2 row_mask:0xf bank_mask:0xf bound_ctrl:1
	s_nop 1
	v_add_f32_dpp v23, v23, v23 row_ror:1 row_mask:0xf bank_mask:0xf bound_ctrl:1
	v_mov_b32_e32 v22, v23
	s_nop 1
	v_permlane16_swap_b32_e32 v23, v22
	v_add_f32_e32 v23, v23, v22
	v_mov_b32_e32 v22, v23
	s_nop 1
	v_permlane32_swap_b32_e32 v23, v22
	v_add_f32_e32 v23, v23, v22
	s_and_saveexec_b64 s[12:13], s[6:7]
	v_mov_b32_e32 v5, v23
	v_fmamk_f32 v5, v5, 0x3a800000, v112
	v_mul_f32_e32 v6, 0x4f800000, v5
	v_cmp_gt_f32_e32 vcc, s67, v5
	v_mul_f32_e32 v4, 0x3a800000, v4
	s_nop 0
	v_cndmask_b32_e32 v5, v5, v6, vcc
	v_sqrt_f32_e32 v6, v5
	s_nop 0
	v_add_u32_e32 v7, -1, v6
	v_fma_f32 v9, -v7, v6, v5
	v_add_u32_e32 v8, 1, v6
	v_cmp_ge_f32_e64 s[8:9], 0, v9
	s_nop 1
	v_cndmask_b32_e64 v7, v6, v7, s[8:9]
	v_fma_f32 v6, -v8, v6, v5
	v_cmp_lt_f32_e64 s[8:9], 0, v6
	s_nop 1
	v_cndmask_b32_e64 v6, v7, v8, s[8:9]
	v_mul_f32_e32 v7, 0x37800000, v6
	v_cndmask_b32_e32 v6, v6, v7, vcc
	v_cmp_class_f32_e32 vcc, v5, v113
	s_nop 1
	v_cndmask_b32_e32 v5, v6, v5, vcc
	v_div_scale_f32 v6, s[8:9], v5, v5, 1.0
	v_rcp_f32_e32 v7, v6
	s_nop 0
	v_fma_f32 v8, -v6, v7, 1.0
	v_fmac_f32_e32 v7, v8, v7
	v_div_scale_f32 v8, vcc, 1.0, v5, 1.0
	v_mul_f32_e32 v9, v8, v7
	v_fma_f32 v10, -v6, v9, v8
	v_fmac_f32_e32 v9, v10, v7
	v_fma_f32 v6, -v6, v9, v8
	s_nop 1
	v_div_fmas_f32 v6, v6, v7, v9
	v_div_fixup_f32 v5, v6, v5, 1.0
	ds_write_b64 v62, v[4:5] offset:104
	s_or_b64 exec, exec, s[12:13]
	s_waitcnt vmcnt(2)
	v_mov_b32_e32 v4, v162
	v_mov_b32_e32 v5, v163
	v_mov_b32_e32 v6, v164
	v_mov_b32_e32 v7, v165
	v_mov_b32_e32 v8, v166
	v_mov_b32_e32 v9, v167
	v_mov_b32_e32 v10, v168
	v_mov_b32_e32 v11, v169
	v_lshlrev_b32_e32 v13, 16, v4
	v_and_b32_e32 v14, 0xffff0000, v4
	v_lshlrev_b32_e32 v15, 16, v5
	v_and_b32_e32 v5, 0xffff0000, v5
	v_lshlrev_b32_e32 v16, 16, v6
	v_and_b32_e32 v6, 0xffff0000, v6
	v_lshlrev_b32_e32 v17, 16, v7
	v_and_b32_e32 v7, 0xffff0000, v7
	v_lshlrev_b32_e32 v18, 16, v8
	v_and_b32_e32 v8, 0xffff0000, v8
	v_lshlrev_b32_e32 v19, 16, v9
	v_and_b32_e32 v9, 0xffff0000, v9
	v_lshlrev_b32_e32 v20, 16, v10
	v_and_b32_e32 v10, 0xffff0000, v10
	v_lshlrev_b32_e32 v21, 16, v11
	v_and_b32_e32 v11, 0xffff0000, v11
	v_add_f32_e32 v22, v13, v14
	v_add_f32_e32 v23, v15, v5
	v_add_f32_e32 v24, v16, v6
	v_add_f32_e32 v25, v17, v7
	v_add_f32_e32 v26, v18, v8
	v_add_f32_e32 v27, v19, v9
	v_add_f32_e32 v12, v20, v10
	v_add_f32_e32 v4, v21, v11
	v_add_f32_e32 v22, v22, v23
	v_add_f32_e32 v24, v24, v25
	v_add_f32_e32 v26, v26, v27
	v_add_f32_e32 v4, v12, v4
	v_add_f32_e32 v22, v22, v24
	v_add_f32_e32 v4, v26, v4
	v_add_f32_e32 v4, v22, v4
	s_nop 1
	v_add_f32_dpp v4, v4, v4 row_ror:8 row_mask:0xf bank_mask:0xf bound_ctrl:1
	s_nop 1
	v_add_f32_dpp v4, v4, v4 row_ror:4 row_mask:0xf bank_mask:0xf bound_ctrl:1
	s_nop 1
	v_add_f32_dpp v4, v4, v4 row_ror:2 row_mask:0xf bank_mask:0xf bound_ctrl:1
	s_nop 1
	v_add_f32_dpp v4, v4, v4 row_ror:1 row_mask:0xf bank_mask:0xf bound_ctrl:1
	v_mov_b32_e32 v22, v4
	s_nop 1
	v_permlane16_swap_b32_e32 v4, v22
	v_add_f32_e32 v4, v4, v22
	v_mov_b32_e32 v22, v4
	s_nop 1
	v_permlane32_swap_b32_e32 v4, v22
	v_add_f32_e32 v4, v4, v22
	v_fmac_f32_e32 v13, 0xba800000, v4
	v_fmac_f32_e32 v14, 0xba800000, v4
	v_fmac_f32_e32 v15, 0xba800000, v4
	v_fmac_f32_e32 v5, 0xba800000, v4
	v_fmac_f32_e32 v16, 0xba800000, v4
	v_fmac_f32_e32 v6, 0xba800000, v4
	v_fmac_f32_e32 v17, 0xba800000, v4
	v_fmac_f32_e32 v7, 0xba800000, v4
	v_fmac_f32_e32 v18, 0xba800000, v4
	v_fmac_f32_e32 v8, 0xba800000, v4
	v_fmac_f32_e32 v19, 0xba800000, v4
	v_fmac_f32_e32 v9, 0xba800000, v4
	v_fmac_f32_e32 v20, 0xba800000, v4
	v_fmac_f32_e32 v10, 0xba800000, v4
	v_fmac_f32_e32 v21, 0xba800000, v4
	v_fmac_f32_e32 v11, 0xba800000, v4
	v_mul_f32_e32 v23, v13, v13
	v_fmac_f32_e32 v23, v14, v14
	v_fmac_f32_e32 v23, v15, v15
	v_fmac_f32_e32 v23, v5, v5
	v_fmac_f32_e32 v23, v16, v16
	v_fmac_f32_e32 v23, v6, v6
	v_fmac_f32_e32 v23, v17, v17
	v_fmac_f32_e32 v23, v7, v7
	v_fmac_f32_e32 v23, v18, v18
	v_fmac_f32_e32 v23, v8, v8
	v_fmac_f32_e32 v23, v19, v19
	v_fmac_f32_e32 v23, v9, v9
	v_fmac_f32_e32 v23, v20, v20
	v_fmac_f32_e32 v23, v10, v10
	v_fmac_f32_e32 v23, v21, v21
	v_fmac_f32_e32 v23, v11, v11
	s_nop 1
	v_add_f32_dpp v23, v23, v23 row_ror:8 row_mask:0xf bank_mask:0xf bound_ctrl:1
	s_nop 1
	v_add_f32_dpp v23, v23, v23 row_ror:4 row_mask:0xf bank_mask:0xf bound_ctrl:1
	s_nop 1
	v_add_f32_dpp v23, v23, v23 row_ror:2 row_mask:0xf bank_mask:0xf bound_ctrl:1
	s_nop 1
	v_add_f32_dpp v23, v23, v23 row_ror:1 row_mask:0xf bank_mask:0xf bound_ctrl:1
	v_mov_b32_e32 v22, v23
	s_nop 1
	v_permlane16_swap_b32_e32 v23, v22
	v_add_f32_e32 v23, v23, v22
	v_mov_b32_e32 v22, v23
	s_nop 1
	v_permlane32_swap_b32_e32 v23, v22
	v_add_f32_e32 v23, v23, v22
	s_and_saveexec_b64 s[12:13], s[6:7]
	v_mov_b32_e32 v5, v23
	v_fmamk_f32 v5, v5, 0x3a800000, v112
	v_mul_f32_e32 v6, 0x4f800000, v5
	v_cmp_gt_f32_e32 vcc, s67, v5
	v_mul_f32_e32 v4, 0x3a800000, v4
	s_nop 0
	v_cndmask_b32_e32 v5, v5, v6, vcc
	v_sqrt_f32_e32 v6, v5
	s_nop 0
	v_add_u32_e32 v7, -1, v6
	v_fma_f32 v9, -v7, v6, v5
	v_add_u32_e32 v8, 1, v6
	v_cmp_ge_f32_e64 s[8:9], 0, v9
	s_nop 1
	v_cndmask_b32_e64 v7, v6, v7, s[8:9]
	v_fma_f32 v6, -v8, v6, v5
	v_cmp_lt_f32_e64 s[8:9], 0, v6
	s_nop 1
	v_cndmask_b32_e64 v6, v7, v8, s[8:9]
	v_mul_f32_e32 v7, 0x37800000, v6
	v_cndmask_b32_e32 v6, v6, v7, vcc
	v_cmp_class_f32_e32 vcc, v5, v113
	s_nop 1
	v_cndmask_b32_e32 v5, v6, v5, vcc
	v_div_scale_f32 v6, s[8:9], v5, v5, 1.0
	v_rcp_f32_e32 v7, v6
	s_nop 0
	v_fma_f32 v8, -v6, v7, 1.0
	v_fmac_f32_e32 v7, v8, v7
	v_div_scale_f32 v8, vcc, 1.0, v5, 1.0
	v_mul_f32_e32 v9, v8, v7
	v_fma_f32 v10, -v6, v9, v8
	v_fmac_f32_e32 v9, v10, v7
	v_fma_f32 v6, -v6, v9, v8
	s_nop 1
	v_div_fmas_f32 v6, v6, v7, v9
	v_div_fixup_f32 v5, v6, v5, 1.0
	ds_write_b64 v62, v[4:5] offset:112
	s_or_b64 exec, exec, s[12:13]
	s_waitcnt vmcnt(0)
	v_mov_b32_e32 v4, v170
	v_mov_b32_e32 v5, v171
	v_mov_b32_e32 v6, v172
	v_mov_b32_e32 v7, v173
	v_mov_b32_e32 v8, v174
	v_mov_b32_e32 v9, v175
	v_mov_b32_e32 v10, v176
	v_mov_b32_e32 v11, v177
	v_lshlrev_b32_e32 v13, 16, v4
	v_and_b32_e32 v14, 0xffff0000, v4
	v_lshlrev_b32_e32 v15, 16, v5
	v_and_b32_e32 v5, 0xffff0000, v5
	v_lshlrev_b32_e32 v16, 16, v6
	v_and_b32_e32 v6, 0xffff0000, v6
	v_lshlrev_b32_e32 v17, 16, v7
	v_and_b32_e32 v7, 0xffff0000, v7
	v_lshlrev_b32_e32 v18, 16, v8
	v_and_b32_e32 v8, 0xffff0000, v8
	v_lshlrev_b32_e32 v19, 16, v9
	v_and_b32_e32 v9, 0xffff0000, v9
	v_lshlrev_b32_e32 v20, 16, v10
	v_and_b32_e32 v10, 0xffff0000, v10
	v_lshlrev_b32_e32 v21, 16, v11
	v_and_b32_e32 v11, 0xffff0000, v11
	v_add_f32_e32 v22, v13, v14
	v_add_f32_e32 v23, v15, v5
	v_add_f32_e32 v24, v16, v6
	v_add_f32_e32 v25, v17, v7
	v_add_f32_e32 v26, v18, v8
	v_add_f32_e32 v27, v19, v9
	v_add_f32_e32 v12, v20, v10
	v_add_f32_e32 v4, v21, v11
	v_add_f32_e32 v22, v22, v23
	v_add_f32_e32 v24, v24, v25
	v_add_f32_e32 v26, v26, v27
	v_add_f32_e32 v4, v12, v4
	v_add_f32_e32 v22, v22, v24
	v_add_f32_e32 v4, v26, v4
	v_add_f32_e32 v4, v22, v4
	s_nop 1
	v_add_f32_dpp v4, v4, v4 row_ror:8 row_mask:0xf bank_mask:0xf bound_ctrl:1
	s_nop 1
	v_add_f32_dpp v4, v4, v4 row_ror:4 row_mask:0xf bank_mask:0xf bound_ctrl:1
	s_nop 1
	v_add_f32_dpp v4, v4, v4 row_ror:2 row_mask:0xf bank_mask:0xf bound_ctrl:1
	s_nop 1
	v_add_f32_dpp v4, v4, v4 row_ror:1 row_mask:0xf bank_mask:0xf bound_ctrl:1
	v_mov_b32_e32 v22, v4
	s_nop 1
	v_permlane16_swap_b32_e32 v4, v22
	v_add_f32_e32 v4, v4, v22
	v_mov_b32_e32 v22, v4
	s_nop 1
	v_permlane32_swap_b32_e32 v4, v22
	v_add_f32_e32 v4, v4, v22
	v_fmac_f32_e32 v13, 0xba800000, v4
	v_fmac_f32_e32 v14, 0xba800000, v4
	v_fmac_f32_e32 v15, 0xba800000, v4
	v_fmac_f32_e32 v5, 0xba800000, v4
	v_fmac_f32_e32 v16, 0xba800000, v4
	v_fmac_f32_e32 v6, 0xba800000, v4
	v_fmac_f32_e32 v17, 0xba800000, v4
	v_fmac_f32_e32 v7, 0xba800000, v4
	v_fmac_f32_e32 v18, 0xba800000, v4
	v_fmac_f32_e32 v8, 0xba800000, v4
	v_fmac_f32_e32 v19, 0xba800000, v4
	v_fmac_f32_e32 v9, 0xba800000, v4
	v_fmac_f32_e32 v20, 0xba800000, v4
	v_fmac_f32_e32 v10, 0xba800000, v4
	v_fmac_f32_e32 v21, 0xba800000, v4
	v_fmac_f32_e32 v11, 0xba800000, v4
	v_mul_f32_e32 v23, v13, v13
	v_fmac_f32_e32 v23, v14, v14
	v_fmac_f32_e32 v23, v15, v15
	v_fmac_f32_e32 v23, v5, v5
	v_fmac_f32_e32 v23, v16, v16
	v_fmac_f32_e32 v23, v6, v6
	v_fmac_f32_e32 v23, v17, v17
	v_fmac_f32_e32 v23, v7, v7
	v_fmac_f32_e32 v23, v18, v18
	v_fmac_f32_e32 v23, v8, v8
	v_fmac_f32_e32 v23, v19, v19
	v_fmac_f32_e32 v23, v9, v9
	v_fmac_f32_e32 v23, v20, v20
	v_fmac_f32_e32 v23, v10, v10
	v_fmac_f32_e32 v23, v21, v21
	v_fmac_f32_e32 v23, v11, v11
	s_nop 1
	v_add_f32_dpp v23, v23, v23 row_ror:8 row_mask:0xf bank_mask:0xf bound_ctrl:1
	s_nop 1
	v_add_f32_dpp v23, v23, v23 row_ror:4 row_mask:0xf bank_mask:0xf bound_ctrl:1
	s_nop 1
	v_add_f32_dpp v23, v23, v23 row_ror:2 row_mask:0xf bank_mask:0xf bound_ctrl:1
	s_nop 1
	v_add_f32_dpp v23, v23, v23 row_ror:1 row_mask:0xf bank_mask:0xf bound_ctrl:1
	v_mov_b32_e32 v22, v23
	s_nop 1
	v_permlane16_swap_b32_e32 v23, v22
	v_add_f32_e32 v23, v23, v22
	v_mov_b32_e32 v22, v23
	s_nop 1
	v_permlane32_swap_b32_e32 v23, v22
	v_add_f32_e32 v23, v23, v22
	s_and_saveexec_b64 s[12:13], s[6:7]
	v_mov_b32_e32 v5, v23
	v_fmamk_f32 v5, v5, 0x3a800000, v112
	v_mul_f32_e32 v6, 0x4f800000, v5
	v_cmp_gt_f32_e32 vcc, s67, v5
	v_mul_f32_e32 v4, 0x3a800000, v4
	s_nop 0
	v_cndmask_b32_e32 v5, v5, v6, vcc
	v_sqrt_f32_e32 v6, v5
	s_nop 0
	v_add_u32_e32 v7, -1, v6
	v_fma_f32 v9, -v7, v6, v5
	v_add_u32_e32 v8, 1, v6
	v_cmp_ge_f32_e64 s[8:9], 0, v9
	s_nop 1
	v_cndmask_b32_e64 v7, v6, v7, s[8:9]
	v_fma_f32 v6, -v8, v6, v5
	v_cmp_lt_f32_e64 s[8:9], 0, v6
	s_nop 1
	v_cndmask_b32_e64 v6, v7, v8, s[8:9]
	v_mul_f32_e32 v7, 0x37800000, v6
	v_cndmask_b32_e32 v6, v6, v7, vcc
	v_cmp_class_f32_e32 vcc, v5, v113
	s_nop 1
	v_cndmask_b32_e32 v5, v6, v5, vcc
	v_div_scale_f32 v6, s[8:9], v5, v5, 1.0
	v_rcp_f32_e32 v7, v6
	s_nop 0
	v_fma_f32 v8, -v6, v7, 1.0
	v_fmac_f32_e32 v7, v8, v7
	v_div_scale_f32 v8, vcc, 1.0, v5, 1.0
	v_mul_f32_e32 v9, v8, v7
	v_fma_f32 v10, -v6, v9, v8
	v_fmac_f32_e32 v9, v10, v7
	v_fma_f32 v6, -v6, v9, v8
	s_nop 1
	v_div_fmas_f32 v6, v6, v7, v9
	v_div_fixup_f32 v5, v6, v5, 1.0
	ds_write_b64 v62, v[4:5] offset:120
	s_or_b64 exec, exec, s[12:13]
.Lgst_done:
.LBB0_742:
	v_lshlrev_b32_e32 v2, 4, v1
	v_and_b32_e32 v2, 0x1f0, v2
	v_add_u32_e32 v22, 0, v2
	v_lshrrev_b32_e32 v2, 1, v0
	s_ashr_i32 s6, s14, 1
	v_and_b32_e32 v23, 24, v2
	v_bfe_u32 v2, v1, 2, 2
	s_and_b32 s60, s6, 0xffffff80
	v_or_b32_e32 v19, v23, v2
	v_lshlrev_b32_e32 v2, 2, v1
	v_and_or_b32 v24, v2, 12, s60
	v_and_b32_e32 v20, 15, v1
	v_mul_u32_u24_e32 v19, 0x220, v19
	v_lshlrev_b32_e32 v24, 1, v24
	v_ashrrev_i32_e32 v21, 5, v1
	s_bfe_u32 s71, s14, 0x20006
	v_add3_u32 v122, 0, v19, v24
	v_and_b32_e32 v24, 31, v1
	v_lshlrev_b32_e32 v1, 8, v20
	v_lshl_or_b32 v1, s71, 13, v1
	v_and_or_b32 v70, v0, 48, v1
	v_add_u32_e32 v0, s3, v21
	v_ashrrev_i32_e32 v1, 31, v0
	v_lshlrev_b64 v[72:73], 12, v[0:1]
	v_add_u32_e32 v0, s40, v21
	v_ashrrev_i32_e32 v1, 31, v0
	v_lshlrev_b64 v[74:75], 12, v[0:1]
	v_add_u32_e32 v0, s41, v21
	v_ashrrev_i32_e32 v1, 31, v0
	v_lshlrev_b64 v[76:77], 12, v[0:1]
	v_add_u32_e32 v0, s62, v21
	v_ashrrev_i32_e32 v1, 31, v0
	v_lshlrev_b64 v[78:79], 12, v[0:1]
	v_add_u32_e32 v0, s63, v21
	v_ashrrev_i32_e32 v1, 31, v0
	v_lshlrev_b64 v[80:81], 12, v[0:1]
	v_add_u32_e32 v0, s64, v21
	v_ashrrev_i32_e32 v1, 31, v0
	s_lshl_b32 s72, s71, 5
	s_ashr_i32 s61, s60, 31
	v_lshlrev_b64 v[82:83], 12, v[0:1]
	v_add_u32_e32 v0, s65, v21
	v_or_b32_e32 v18, s72, v20
	s_cmp_lg_u32 s71, 0
	v_ashrrev_i32_e32 v1, 31, v0
	v_add_u32_e32 v25, 16, v21
	v_add_u32_e32 v26, 32, v21
	v_add_u32_e32 v27, 48, v21
	v_add_u32_e32 v28, 64, v21
	v_add_u32_e32 v29, 0x50, v21
	v_add_u32_e32 v30, 0x60, v21
	v_add_u32_e32 v31, 0x70, v21
	s_cselect_b64 s[54:55], -1, 0
	s_cmp_gt_u32 s71, 1
	v_or_b32_e32 v19, 16, v18
	v_lshlrev_b32_e32 v64, 2, v18
	v_lshlrev_b64 v[84:85], 12, v[0:1]
	v_add_u32_e32 v0, s66, v21
	v_cmp_gt_i32_e64 s[6:7], s24, v21
	v_cmp_gt_i32_e64 s[8:9], s24, v25
	v_cmp_gt_i32_e64 s[10:11], s24, v26
	v_cmp_gt_i32_e64 s[12:13], s24, v27
	v_cmp_gt_i32_e64 s[14:15], s24, v28
	v_cmp_gt_i32_e64 s[16:17], s24, v29
	v_cmp_gt_i32_e64 s[18:19], s24, v30
	v_cmp_gt_i32_e64 s[20:21], s24, v31
	s_cselect_b64 s[56:57], -1, 0
	s_cmp_eq_u32 s71, 3
	v_cmp_gt_u32_e64 s[22:23], s24, v18
	v_cmp_gt_u32_e64 s[24:25], s24, v19
	v_lshl_add_u64 v[18:19], s[26:27], 0, v[64:65]
	v_lshlrev_b32_e32 v64, 5, v24
	v_ashrrev_i32_e32 v1, 31, v0
	v_add_u32_e32 v2, s70, v21
	v_add_u32_e32 v4, s70, v25
	s_waitcnt lgkmcnt(0)
	v_add_u32_e32 v6, s70, v26
	v_add_u32_e32 v8, s70, v27
	v_add_u32_e32 v10, s70, v28
	v_add_u32_e32 v12, s70, v29
	v_add_u32_e32 v14, s70, v30
	v_add_u32_e32 v16, s70, v31
	s_cselect_b64 s[58:59], -1, 0
	v_lshlrev_b64 v[86:87], 12, v[0:1]
	v_lshl_add_u64 v[0:1], s[38:39], 0, v[64:65]
	s_add_i32 s70, s70, s72
	v_lshl_add_u64 v[88:89], v[0:1], 0, 16
	v_add_u32_e32 v0, s70, v20
	v_ashrrev_i32_e32 v1, 31, v0
	v_lshlrev_b64 v[0:1], 11, v[0:1]
	v_or_b32_e32 v0, v0, v23
	s_lshl_b64 s[26:27], s[60:61], 1
	v_lshl_add_u64 v[0:1], v[0:1], 0, s[26:27]
	v_lshl_add_u64 v[94:95], v[0:1], 0, s[46:47]
	v_add3_u32 v0, s70, 16, v20
	v_ashrrev_i32_e32 v1, 31, v0
	v_lshlrev_b64 v[0:1], 11, v[0:1]
	v_or_b32_e32 v0, v0, v23
	v_lshlrev_b32_e32 v32, 3, v21
	v_lshl_add_u64 v[0:1], v[0:1], 0, s[26:27]
	v_lshlrev_b32_e32 v25, 3, v25
	v_lshl_add_u64 v[108:109], v[0:1], 0, s[46:47]
	v_add_u32_e32 v0, 0, v32
	v_lshlrev_b32_e32 v26, 3, v26
	v_lshl_add_u64 v[66:67], v[18:19], 0, 64
	v_lshl_add_u64 v[18:19], s[36:37], 0, v[64:65]
	v_or_b32_e32 v72, v72, v64
	v_or_b32_e32 v74, v74, v64
	v_or_b32_e32 v76, v76, v64
	v_or_b32_e32 v78, v78, v64
	v_or_b32_e32 v80, v80, v64
	v_or_b32_e32 v82, v82, v64
	v_or_b32_e32 v84, v84, v64
	v_or_b32_e32 v86, v86, v64
	v_add_u32_e32 v64, 0x20000, v0
	v_add_u32_e32 v0, 0, v25
	v_lshlrev_b32_e32 v27, 3, v27
	v_add_u32_e32 v123, 0x20000, v0
	v_add_u32_e32 v0, 0, v26
	v_lshlrev_b32_e32 v28, 3, v28
	v_add_u32_e32 v124, 0x20000, v0
	v_add_u32_e32 v0, 0, v27
	v_lshlrev_b32_e32 v29, 3, v29
	v_add_u32_e32 v125, 0x20000, v0
	v_add_u32_e32 v0, 0, v28
	v_ashrrev_i32_e32 v3, 31, v2
	v_ashrrev_i32_e32 v5, 31, v4
	v_ashrrev_i32_e32 v7, 31, v6
	v_ashrrev_i32_e32 v9, 31, v8
	v_ashrrev_i32_e32 v11, 31, v10
	v_ashrrev_i32_e32 v13, 31, v12
	v_ashrrev_i32_e32 v15, 31, v14
	v_ashrrev_i32_e32 v17, 31, v16
	v_lshlrev_b32_e32 v30, 3, v30
	v_add_u32_e32 v126, 0x20000, v0
	v_add_u32_e32 v0, 0, v29
	v_lshlrev_b64 v[2:3], 11, v[2:3]
	v_lshlrev_b64 v[4:5], 11, v[4:5]
	v_lshlrev_b64 v[6:7], 11, v[6:7]
	v_lshlrev_b64 v[8:9], 11, v[8:9]
	v_lshlrev_b64 v[10:11], 11, v[10:11]
	v_lshlrev_b64 v[12:13], 11, v[12:13]
	v_lshlrev_b64 v[14:15], 11, v[14:15]
	v_lshlrev_b64 v[16:17], 11, v[16:17]
	v_lshlrev_b32_e32 v31, 3, v31
	v_lshl_add_u64 v[68:69], v[18:19], 0, 16
	v_lshlrev_b32_e32 v18, 4, v24
	v_add_u32_e32 v127, 0x20000, v0
	v_add_u32_e32 v0, 0, v30
	v_mul_lo_u32 v33, v21, s68
	v_or_b32_e32 v16, v16, v18
	v_or_b32_e32 v14, v14, v18
	v_or_b32_e32 v12, v12, v18
	v_or_b32_e32 v10, v10, v18
	v_or_b32_e32 v8, v8, v18
	v_or_b32_e32 v6, v6, v18
	v_or_b32_e32 v4, v4, v18
	v_or_b32_e32 v2, v2, v18
	v_add_u32_e32 v128, 0x20000, v0
	v_add_u32_e32 v0, 0, v31
	v_mov_b32_e32 v71, v65
	v_lshl_add_u64 v[90:91], v[16:17], 0, s[44:45]
	v_lshl_add_u64 v[92:93], v[14:15], 0, s[44:45]
	v_lshl_add_u64 v[96:97], v[12:13], 0, s[44:45]
	v_lshl_add_u64 v[98:99], v[10:11], 0, s[44:45]
	v_lshl_add_u64 v[100:101], v[8:9], 0, s[44:45]
	v_lshl_add_u64 v[102:103], v[6:7], 0, s[44:45]
	v_lshl_add_u64 v[104:105], v[4:5], 0, s[44:45]
	v_lshl_add_u64 v[106:107], v[2:3], 0, s[44:45]
	s_mov_b64 s[36:37], 0
	v_add_u32_e32 v129, 0x20000, v0
	v_add_u32_e32 v130, v22, v33
	s_cmp_eq_u32 s98, 0
	s_cbranch_scc1 .Lgt_g0
	s_lshl_b32 s36, s98, 10
	s_lshl_b32 s100, s98, 9
	s_mov_b32 s101, 0
	v_lshl_add_u64 v[66:67], v[66:67], 0, s[100:101]
	v_lshl_add_u64 v[90:91], v[90:91], 0, s[100:101]
	v_lshl_add_u64 v[92:93], v[92:93], 0, s[100:101]
	v_lshl_add_u64 v[94:95], v[94:95], 0, s[100:101]
	v_lshl_add_u64 v[96:97], v[96:97], 0, s[100:101]
	v_lshl_add_u64 v[98:99], v[98:99], 0, s[100:101]
	v_lshl_add_u64 v[100:101], v[100:101], 0, s[100:101]
	v_lshl_add_u64 v[102:103], v[102:103], 0, s[100:101]
	v_lshl_add_u64 v[104:105], v[104:105], 0, s[100:101]
	v_lshl_add_u64 v[106:107], v[106:107], 0, s[100:101]
	v_lshl_add_u64 v[108:109], v[108:109], 0, s[100:101]
	s_lshl_b32 s100, s98, 15
	v_lshl_add_u64 v[70:71], v[70:71], 0, s[100:101]
.Lgt_g0:
	s_barrier
	s_branch .LBB0_744
.LBB0_743:
	s_or_b64 exec, exec, s[26:27]
	s_add_u32 s36, s36, 0x400
	s_addc_u32 s37, s37, 0
	v_lshl_add_u64 v[66:67], v[66:67], 0, s[48:49]
	v_lshl_add_u64 v[70:71], v[70:71], 0, s[50:51]
	v_lshl_add_u64 v[90:91], v[90:91], 0, s[48:49]
	v_lshl_add_u64 v[92:93], v[92:93], 0, s[48:49]
	v_lshl_add_u64 v[94:95], v[94:95], 0, s[48:49]
	v_lshl_add_u64 v[96:97], v[96:97], 0, s[48:49]
	v_lshl_add_u64 v[98:99], v[98:99], 0, s[48:49]
	v_lshl_add_u64 v[100:101], v[100:101], 0, s[48:49]
	v_lshl_add_u64 v[102:103], v[102:103], 0, s[48:49]
	v_lshl_add_u64 v[104:105], v[104:105], 0, s[48:49]
	v_lshl_add_u64 v[106:107], v[106:107], 0, s[48:49]
	s_cmp_lg_u32 s36, s99
	v_lshl_add_u64 v[108:109], v[108:109], 0, s[48:49]
	s_barrier
	s_cbranch_scc0 .LBB0_735
